# MG merge epilogue: gate loads software-pipelined over the 8 row groups (next group's loads in flight during the current group's exp/rcp math; was 4 rounds each behind its own wait)
# speedup vs baseline: 1.0015x; 1.0015x over previous
.LBB0_1421:
	v_mov_b32_e32 v112, v246
	s_lshl_b32 s6, s18, 8
	v_lshrrev_b32_e32 v114, 1, v112
	v_and_or_b32 v112, v112, 15, s54
	v_and_or_b32 v114, v114, 24, s6
	s_lshl_b32 s6, s19, 10
	v_lshl_add_u32 v112, s60, 8, v112
	v_mov_b64_e32 v[144:145], s[30:31]
	s_ashr_i32 s7, s6, 31
	v_mad_i64_i32 v[150:151], s[36:37], v112, s33, v[144:145]
	v_or_b32_e32 v114, s55, v114
	v_lshl_add_u64 v[144:145], s[6:7], 1, v[150:151]
	s_mov_b64 s[36:37], 0x1e00
	v_lshl_add_u64 v[166:167], v[144:145], 0, s[36:37]
	v_ashrrev_i32_e32 v115, 31, v114
	v_lshl_add_u64 v[146:147], v[114:115], 1, v[166:167]
	v_mov_b64_e32 v[214:215], v[146:147]
	v_lshl_add_u64 v[216:217], v[114:115], 1, v[150:151]
	s_mov_b64 s[98:99], 0x1000
	v_lshl_add_u64 v[216:217], v[216:217], 0, s[98:99]
	s_cmp_lt_i32 s19, 2
	s_cselect_b64 s[46:47], -1, 0
	s_cbranch_scc0 .Lmgepi_last
	v_mov_b64_e32 v[210:211], v[214:215]
	global_load_dwordx4 v[144:147], v[210:211], off
	global_load_dwordx4 v[148:151], v[210:211], off offset:256
	global_load_dwordx4 v[152:155], v[210:211], off offset:2048
	global_load_dwordx4 v[156:159], v[210:211], off offset:2304
	s_mov_b64 s[98:99], 0x36000
	v_lshl_add_u64 v[210:211], v[214:215], 0, s[98:99]
	global_load_dwordx4 v[160:163], v[210:211], off
	global_load_dwordx4 v[164:167], v[210:211], off offset:256
	global_load_dwordx4 v[170:173], v[210:211], off offset:2048
	global_load_dwordx4 v[174:177], v[210:211], off offset:2304
	s_waitcnt vmcnt(4)
	v_lshlrev_b32_e32 v178, 16, v144
	v_and_b32_e32 v144, 0xffff0000, v144
	v_lshlrev_b32_e32 v179, 16, v145
	v_and_b32_e32 v145, 0xffff0000, v145
	v_lshlrev_b32_e32 v180, 16, v146
	v_and_b32_e32 v146, 0xffff0000, v146
	v_lshlrev_b32_e32 v181, 16, v147
	v_and_b32_e32 v147, 0xffff0000, v147
	v_mul_f32_e32 v178, 0xbfb8aa3b, v178
	v_mul_f32_e32 v144, 0xbfb8aa3b, v144
	v_mul_f32_e32 v179, 0xbfb8aa3b, v179
	v_mul_f32_e32 v145, 0xbfb8aa3b, v145
	v_mul_f32_e32 v180, 0xbfb8aa3b, v180
	v_mul_f32_e32 v146, 0xbfb8aa3b, v146
	v_mul_f32_e32 v181, 0xbfb8aa3b, v181
	v_mul_f32_e32 v147, 0xbfb8aa3b, v147
	v_exp_f32_e32 v178, v178
	v_exp_f32_e32 v144, v144
	v_exp_f32_e32 v179, v179
	v_exp_f32_e32 v145, v145
	v_exp_f32_e32 v180, v180
	v_exp_f32_e32 v146, v146
	v_exp_f32_e32 v181, v181
	v_exp_f32_e32 v147, v147
	v_lshlrev_b32_e32 v182, 16, v152
	v_and_b32_e32 v152, 0xffff0000, v152
	v_lshlrev_b32_e32 v183, 16, v153
	v_and_b32_e32 v153, 0xffff0000, v153
	v_lshlrev_b32_e32 v184, 16, v154
	v_and_b32_e32 v154, 0xffff0000, v154
	v_lshlrev_b32_e32 v185, 16, v155
	v_and_b32_e32 v155, 0xffff0000, v155
	v_mul_f32_e32 v182, 0xbfb8aa3b, v182
	v_mul_f32_e32 v152, 0xbfb8aa3b, v152
	v_mul_f32_e32 v183, 0xbfb8aa3b, v183
	v_mul_f32_e32 v153, 0xbfb8aa3b, v153
	v_mul_f32_e32 v184, 0xbfb8aa3b, v184
	v_mul_f32_e32 v154, 0xbfb8aa3b, v154
	v_mul_f32_e32 v185, 0xbfb8aa3b, v185
	v_mul_f32_e32 v155, 0xbfb8aa3b, v155
	v_exp_f32_e32 v182, v182
	v_exp_f32_e32 v152, v152
	v_exp_f32_e32 v183, v183
	v_exp_f32_e32 v153, v153
	v_exp_f32_e32 v184, v184
	v_exp_f32_e32 v154, v154
	v_exp_f32_e32 v185, v185
	v_exp_f32_e32 v155, v155
	v_add_f32_e32 v178, 1.0, v178
	v_add_f32_e32 v144, 1.0, v144
	v_add_f32_e32 v179, 1.0, v179
	v_add_f32_e32 v145, 1.0, v145
	v_add_f32_e32 v180, 1.0, v180
	v_add_f32_e32 v146, 1.0, v146
	v_add_f32_e32 v181, 1.0, v181
	v_add_f32_e32 v147, 1.0, v147
	v_add_f32_e32 v182, 1.0, v182
	v_add_f32_e32 v152, 1.0, v152
	v_add_f32_e32 v183, 1.0, v183
	v_add_f32_e32 v153, 1.0, v153
	v_add_f32_e32 v184, 1.0, v184
	v_add_f32_e32 v154, 1.0, v154
	v_add_f32_e32 v185, 1.0, v185
	v_add_f32_e32 v155, 1.0, v155
	v_rcp_f32_e32 v178, v178
	v_rcp_f32_e32 v144, v144
	v_rcp_f32_e32 v179, v179
	v_rcp_f32_e32 v145, v145
	v_rcp_f32_e32 v180, v180
	v_rcp_f32_e32 v146, v146
	v_rcp_f32_e32 v181, v181
	v_rcp_f32_e32 v147, v147
	s_nop 0
	v_mul_f32_e32 v186, v178, v182
	v_mul_f32_e32 v187, v144, v152
	v_mul_f32_e32 v188, v179, v183
	v_mul_f32_e32 v189, v145, v153
	v_mul_f32_e32 v190, v180, v184
	v_mul_f32_e32 v191, v146, v154
	v_mul_f32_e32 v192, v181, v185
	v_mul_f32_e32 v193, v147, v155
	v_pk_mul_f32 v[128:129], v[128:129], v[186:187]
	v_pk_mul_f32 v[130:131], v[130:131], v[188:189]
	v_pk_mul_f32 v[124:125], v[124:125], v[190:191]
	v_pk_mul_f32 v[126:127], v[126:127], v[192:193]
	v_lshlrev_b32_e32 v178, 16, v148
	v_and_b32_e32 v148, 0xffff0000, v148
	v_lshlrev_b32_e32 v179, 16, v149
	v_and_b32_e32 v149, 0xffff0000, v149
	v_lshlrev_b32_e32 v180, 16, v150
	v_and_b32_e32 v150, 0xffff0000, v150
	v_lshlrev_b32_e32 v181, 16, v151
	v_and_b32_e32 v151, 0xffff0000, v151
	v_mul_f32_e32 v178, 0xbfb8aa3b, v178
	v_mul_f32_e32 v148, 0xbfb8aa3b, v148
	v_mul_f32_e32 v179, 0xbfb8aa3b, v179
	v_mul_f32_e32 v149, 0xbfb8aa3b, v149
	v_mul_f32_e32 v180, 0xbfb8aa3b, v180
	v_mul_f32_e32 v150, 0xbfb8aa3b, v150
	v_mul_f32_e32 v181, 0xbfb8aa3b, v181
	v_mul_f32_e32 v151, 0xbfb8aa3b, v151
	v_exp_f32_e32 v178, v178
	v_exp_f32_e32 v148, v148
	v_exp_f32_e32 v179, v179
	v_exp_f32_e32 v149, v149
	v_exp_f32_e32 v180, v180
	v_exp_f32_e32 v150, v150
	v_exp_f32_e32 v181, v181
	v_exp_f32_e32 v151, v151
	v_lshlrev_b32_e32 v182, 16, v156
	v_and_b32_e32 v156, 0xffff0000, v156
	v_lshlrev_b32_e32 v183, 16, v157
	v_and_b32_e32 v157, 0xffff0000, v157
	v_lshlrev_b32_e32 v184, 16, v158
	v_and_b32_e32 v158, 0xffff0000, v158
	v_lshlrev_b32_e32 v185, 16, v159
	v_and_b32_e32 v159, 0xffff0000, v159
	v_mul_f32_e32 v182, 0xbfb8aa3b, v182
	v_mul_f32_e32 v156, 0xbfb8aa3b, v156
	v_mul_f32_e32 v183, 0xbfb8aa3b, v183
	v_mul_f32_e32 v157, 0xbfb8aa3b, v157
	v_mul_f32_e32 v184, 0xbfb8aa3b, v184
	v_mul_f32_e32 v158, 0xbfb8aa3b, v158
	v_mul_f32_e32 v185, 0xbfb8aa3b, v185
	v_mul_f32_e32 v159, 0xbfb8aa3b, v159
	v_exp_f32_e32 v182, v182
	v_exp_f32_e32 v156, v156
	v_exp_f32_e32 v183, v183
	v_exp_f32_e32 v157, v157
	v_exp_f32_e32 v184, v184
	v_exp_f32_e32 v158, v158
	v_exp_f32_e32 v185, v185
	v_exp_f32_e32 v159, v159
	v_add_f32_e32 v178, 1.0, v178
	v_add_f32_e32 v148, 1.0, v148
	v_add_f32_e32 v179, 1.0, v179
	v_add_f32_e32 v149, 1.0, v149
	v_add_f32_e32 v180, 1.0, v180
	v_add_f32_e32 v150, 1.0, v150
	v_add_f32_e32 v181, 1.0, v181
	v_add_f32_e32 v151, 1.0, v151
	v_add_f32_e32 v182, 1.0, v182
	v_add_f32_e32 v156, 1.0, v156
	v_add_f32_e32 v183, 1.0, v183
	v_add_f32_e32 v157, 1.0, v157
	v_add_f32_e32 v184, 1.0, v184
	v_add_f32_e32 v158, 1.0, v158
	v_add_f32_e32 v185, 1.0, v185
	v_add_f32_e32 v159, 1.0, v159
	v_rcp_f32_e32 v178, v178
	v_rcp_f32_e32 v148, v148
	v_rcp_f32_e32 v179, v179
	v_rcp_f32_e32 v149, v149
	v_rcp_f32_e32 v180, v180
	v_rcp_f32_e32 v150, v150
	v_rcp_f32_e32 v181, v181
	v_rcp_f32_e32 v151, v151
	s_nop 0
	v_mul_f32_e32 v186, v178, v182
	v_mul_f32_e32 v187, v148, v156
	v_mul_f32_e32 v188, v179, v183
	v_mul_f32_e32 v189, v149, v157
	v_mul_f32_e32 v190, v180, v184
	v_mul_f32_e32 v191, v150, v158
	v_mul_f32_e32 v192, v181, v185
	v_mul_f32_e32 v193, v151, v159
	v_pk_mul_f32 v[92:93], v[92:93], v[186:187]
	v_pk_mul_f32 v[94:95], v[94:95], v[188:189]
	v_pk_mul_f32 v[88:89], v[88:89], v[190:191]
	v_pk_mul_f32 v[90:91], v[90:91], v[192:193]
	s_mov_b64 s[98:99], 0x6c000
	v_lshl_add_u64 v[210:211], v[214:215], 0, s[98:99]
	global_load_dwordx4 v[144:147], v[210:211], off
	global_load_dwordx4 v[148:151], v[210:211], off offset:256
	global_load_dwordx4 v[152:155], v[210:211], off offset:2048
	global_load_dwordx4 v[156:159], v[210:211], off offset:2304
	s_waitcnt vmcnt(4)
	v_lshlrev_b32_e32 v178, 16, v160
	v_and_b32_e32 v160, 0xffff0000, v160
	v_lshlrev_b32_e32 v179, 16, v161
	v_and_b32_e32 v161, 0xffff0000, v161
	v_lshlrev_b32_e32 v180, 16, v162
	v_and_b32_e32 v162, 0xffff0000, v162
	v_lshlrev_b32_e32 v181, 16, v163
	v_and_b32_e32 v163, 0xffff0000, v163
	v_mul_f32_e32 v178, 0xbfb8aa3b, v178
	v_mul_f32_e32 v160, 0xbfb8aa3b, v160
	v_mul_f32_e32 v179, 0xbfb8aa3b, v179
	v_mul_f32_e32 v161, 0xbfb8aa3b, v161
	v_mul_f32_e32 v180, 0xbfb8aa3b, v180
	v_mul_f32_e32 v162, 0xbfb8aa3b, v162
	v_mul_f32_e32 v181, 0xbfb8aa3b, v181
	v_mul_f32_e32 v163, 0xbfb8aa3b, v163
	v_exp_f32_e32 v178, v178
	v_exp_f32_e32 v160, v160
	v_exp_f32_e32 v179, v179
	v_exp_f32_e32 v161, v161
	v_exp_f32_e32 v180, v180
	v_exp_f32_e32 v162, v162
	v_exp_f32_e32 v181, v181
	v_exp_f32_e32 v163, v163
	v_lshlrev_b32_e32 v182, 16, v170
	v_and_b32_e32 v170, 0xffff0000, v170
	v_lshlrev_b32_e32 v183, 16, v171
	v_and_b32_e32 v171, 0xffff0000, v171
	v_lshlrev_b32_e32 v184, 16, v172
	v_and_b32_e32 v172, 0xffff0000, v172
	v_lshlrev_b32_e32 v185, 16, v173
	v_and_b32_e32 v173, 0xffff0000, v173
	v_mul_f32_e32 v182, 0xbfb8aa3b, v182
	v_mul_f32_e32 v170, 0xbfb8aa3b, v170
	v_mul_f32_e32 v183, 0xbfb8aa3b, v183
	v_mul_f32_e32 v171, 0xbfb8aa3b, v171
	v_mul_f32_e32 v184, 0xbfb8aa3b, v184
	v_mul_f32_e32 v172, 0xbfb8aa3b, v172
	v_mul_f32_e32 v185, 0xbfb8aa3b, v185
	v_mul_f32_e32 v173, 0xbfb8aa3b, v173
	v_exp_f32_e32 v182, v182
	v_exp_f32_e32 v170, v170
	v_exp_f32_e32 v183, v183
	v_exp_f32_e32 v171, v171
	v_exp_f32_e32 v184, v184
	v_exp_f32_e32 v172, v172
	v_exp_f32_e32 v185, v185
	v_exp_f32_e32 v173, v173
	v_add_f32_e32 v178, 1.0, v178
	v_add_f32_e32 v160, 1.0, v160
	v_add_f32_e32 v179, 1.0, v179
	v_add_f32_e32 v161, 1.0, v161
	v_add_f32_e32 v180, 1.0, v180
	v_add_f32_e32 v162, 1.0, v162
	v_add_f32_e32 v181, 1.0, v181
	v_add_f32_e32 v163, 1.0, v163
	v_add_f32_e32 v182, 1.0, v182
	v_add_f32_e32 v170, 1.0, v170
	v_add_f32_e32 v183, 1.0, v183
	v_add_f32_e32 v171, 1.0, v171
	v_add_f32_e32 v184, 1.0, v184
	v_add_f32_e32 v172, 1.0, v172
	v_add_f32_e32 v185, 1.0, v185
	v_add_f32_e32 v173, 1.0, v173
	v_rcp_f32_e32 v178, v178
	v_rcp_f32_e32 v160, v160
	v_rcp_f32_e32 v179, v179
	v_rcp_f32_e32 v161, v161
	v_rcp_f32_e32 v180, v180
	v_rcp_f32_e32 v162, v162
	v_rcp_f32_e32 v181, v181
	v_rcp_f32_e32 v163, v163
	s_nop 0
	v_mul_f32_e32 v186, v178, v182
	v_mul_f32_e32 v187, v160, v170
	v_mul_f32_e32 v188, v179, v183
	v_mul_f32_e32 v189, v161, v171
	v_mul_f32_e32 v190, v180, v184
	v_mul_f32_e32 v191, v162, v172
	v_mul_f32_e32 v192, v181, v185
	v_mul_f32_e32 v193, v163, v173
	v_pk_mul_f32 v[120:121], v[120:121], v[186:187]
	v_pk_mul_f32 v[122:123], v[122:123], v[188:189]
	v_pk_mul_f32 v[116:117], v[116:117], v[190:191]
	v_pk_mul_f32 v[118:119], v[118:119], v[192:193]
	v_lshlrev_b32_e32 v178, 16, v164
	v_and_b32_e32 v164, 0xffff0000, v164
	v_lshlrev_b32_e32 v179, 16, v165
	v_and_b32_e32 v165, 0xffff0000, v165
	v_lshlrev_b32_e32 v180, 16, v166
	v_and_b32_e32 v166, 0xffff0000, v166
	v_lshlrev_b32_e32 v181, 16, v167
	v_and_b32_e32 v167, 0xffff0000, v167
	v_mul_f32_e32 v178, 0xbfb8aa3b, v178
	v_mul_f32_e32 v164, 0xbfb8aa3b, v164
	v_mul_f32_e32 v179, 0xbfb8aa3b, v179
	v_mul_f32_e32 v165, 0xbfb8aa3b, v165
	v_mul_f32_e32 v180, 0xbfb8aa3b, v180
	v_mul_f32_e32 v166, 0xbfb8aa3b, v166
	v_mul_f32_e32 v181, 0xbfb8aa3b, v181
	v_mul_f32_e32 v167, 0xbfb8aa3b, v167
	v_exp_f32_e32 v178, v178
	v_exp_f32_e32 v164, v164
	v_exp_f32_e32 v179, v179
	v_exp_f32_e32 v165, v165
	v_exp_f32_e32 v180, v180
	v_exp_f32_e32 v166, v166
	v_exp_f32_e32 v181, v181
	v_exp_f32_e32 v167, v167
	v_lshlrev_b32_e32 v182, 16, v174
	v_and_b32_e32 v174, 0xffff0000, v174
	v_lshlrev_b32_e32 v183, 16, v175
	v_and_b32_e32 v175, 0xffff0000, v175
	v_lshlrev_b32_e32 v184, 16, v176
	v_and_b32_e32 v176, 0xffff0000, v176
	v_lshlrev_b32_e32 v185, 16, v177
	v_and_b32_e32 v177, 0xffff0000, v177
	v_mul_f32_e32 v182, 0xbfb8aa3b, v182
	v_mul_f32_e32 v174, 0xbfb8aa3b, v174
	v_mul_f32_e32 v183, 0xbfb8aa3b, v183
	v_mul_f32_e32 v175, 0xbfb8aa3b, v175
	v_mul_f32_e32 v184, 0xbfb8aa3b, v184
	v_mul_f32_e32 v176, 0xbfb8aa3b, v176
	v_mul_f32_e32 v185, 0xbfb8aa3b, v185
	v_mul_f32_e32 v177, 0xbfb8aa3b, v177
	v_exp_f32_e32 v182, v182
	v_exp_f32_e32 v174, v174
	v_exp_f32_e32 v183, v183
	v_exp_f32_e32 v175, v175
	v_exp_f32_e32 v184, v184
	v_exp_f32_e32 v176, v176
	v_exp_f32_e32 v185, v185
	v_exp_f32_e32 v177, v177
	v_add_f32_e32 v178, 1.0, v178
	v_add_f32_e32 v164, 1.0, v164
	v_add_f32_e32 v179, 1.0, v179
	v_add_f32_e32 v165, 1.0, v165
	v_add_f32_e32 v180, 1.0, v180
	v_add_f32_e32 v166, 1.0, v166
	v_add_f32_e32 v181, 1.0, v181
	v_add_f32_e32 v167, 1.0, v167
	v_add_f32_e32 v182, 1.0, v182
	v_add_f32_e32 v174, 1.0, v174
	v_add_f32_e32 v183, 1.0, v183
	v_add_f32_e32 v175, 1.0, v175
	v_add_f32_e32 v184, 1.0, v184
	v_add_f32_e32 v176, 1.0, v176
	v_add_f32_e32 v185, 1.0, v185
	v_add_f32_e32 v177, 1.0, v177
	v_rcp_f32_e32 v178, v178
	v_rcp_f32_e32 v164, v164
	v_rcp_f32_e32 v179, v179
	v_rcp_f32_e32 v165, v165
	v_rcp_f32_e32 v180, v180
	v_rcp_f32_e32 v166, v166
	v_rcp_f32_e32 v181, v181
	v_rcp_f32_e32 v167, v167
	s_nop 0
	v_mul_f32_e32 v186, v178, v182
	v_mul_f32_e32 v187, v164, v174
	v_mul_f32_e32 v188, v179, v183
	v_mul_f32_e32 v189, v165, v175
	v_mul_f32_e32 v190, v180, v184
	v_mul_f32_e32 v191, v166, v176
	v_mul_f32_e32 v192, v181, v185
	v_mul_f32_e32 v193, v167, v177
	v_pk_mul_f32 v[84:85], v[84:85], v[186:187]
	v_pk_mul_f32 v[86:87], v[86:87], v[188:189]
	v_pk_mul_f32 v[80:81], v[80:81], v[190:191]
	v_pk_mul_f32 v[82:83], v[82:83], v[192:193]
	s_mov_b64 s[98:99], 0xa2000
	v_lshl_add_u64 v[210:211], v[214:215], 0, s[98:99]
	global_load_dwordx4 v[160:163], v[210:211], off
	global_load_dwordx4 v[164:167], v[210:211], off offset:256
	global_load_dwordx4 v[170:173], v[210:211], off offset:2048
	global_load_dwordx4 v[174:177], v[210:211], off offset:2304
	s_waitcnt vmcnt(4)
	v_lshlrev_b32_e32 v178, 16, v144
	v_and_b32_e32 v144, 0xffff0000, v144
	v_lshlrev_b32_e32 v179, 16, v145
	v_and_b32_e32 v145, 0xffff0000, v145
	v_lshlrev_b32_e32 v180, 16, v146
	v_and_b32_e32 v146, 0xffff0000, v146
	v_lshlrev_b32_e32 v181, 16, v147
	v_and_b32_e32 v147, 0xffff0000, v147
	v_mul_f32_e32 v178, 0xbfb8aa3b, v178
	v_mul_f32_e32 v144, 0xbfb8aa3b, v144
	v_mul_f32_e32 v179, 0xbfb8aa3b, v179
	v_mul_f32_e32 v145, 0xbfb8aa3b, v145
	v_mul_f32_e32 v180, 0xbfb8aa3b, v180
	v_mul_f32_e32 v146, 0xbfb8aa3b, v146
	v_mul_f32_e32 v181, 0xbfb8aa3b, v181
	v_mul_f32_e32 v147, 0xbfb8aa3b, v147
	v_exp_f32_e32 v178, v178
	v_exp_f32_e32 v144, v144
	v_exp_f32_e32 v179, v179
	v_exp_f32_e32 v145, v145
	v_exp_f32_e32 v180, v180
	v_exp_f32_e32 v146, v146
	v_exp_f32_e32 v181, v181
	v_exp_f32_e32 v147, v147
	v_lshlrev_b32_e32 v182, 16, v152
	v_and_b32_e32 v152, 0xffff0000, v152
	v_lshlrev_b32_e32 v183, 16, v153
	v_and_b32_e32 v153, 0xffff0000, v153
	v_lshlrev_b32_e32 v184, 16, v154
	v_and_b32_e32 v154, 0xffff0000, v154
	v_lshlrev_b32_e32 v185, 16, v155
	v_and_b32_e32 v155, 0xffff0000, v155
	v_mul_f32_e32 v182, 0xbfb8aa3b, v182
	v_mul_f32_e32 v152, 0xbfb8aa3b, v152
	v_mul_f32_e32 v183, 0xbfb8aa3b, v183
	v_mul_f32_e32 v153, 0xbfb8aa3b, v153
	v_mul_f32_e32 v184, 0xbfb8aa3b, v184
	v_mul_f32_e32 v154, 0xbfb8aa3b, v154
	v_mul_f32_e32 v185, 0xbfb8aa3b, v185
	v_mul_f32_e32 v155, 0xbfb8aa3b, v155
	v_exp_f32_e32 v182, v182
	v_exp_f32_e32 v152, v152
	v_exp_f32_e32 v183, v183
	v_exp_f32_e32 v153, v153
	v_exp_f32_e32 v184, v184
	v_exp_f32_e32 v154, v154
	v_exp_f32_e32 v185, v185
	v_exp_f32_e32 v155, v155
	v_add_f32_e32 v178, 1.0, v178
	v_add_f32_e32 v144, 1.0, v144
	v_add_f32_e32 v179, 1.0, v179
	v_add_f32_e32 v145, 1.0, v145
	v_add_f32_e32 v180, 1.0, v180
	v_add_f32_e32 v146, 1.0, v146
	v_add_f32_e32 v181, 1.0, v181
	v_add_f32_e32 v147, 1.0, v147
	v_add_f32_e32 v182, 1.0, v182
	v_add_f32_e32 v152, 1.0, v152
	v_add_f32_e32 v183, 1.0, v183
	v_add_f32_e32 v153, 1.0, v153
	v_add_f32_e32 v184, 1.0, v184
	v_add_f32_e32 v154, 1.0, v154
	v_add_f32_e32 v185, 1.0, v185
	v_add_f32_e32 v155, 1.0, v155
	v_rcp_f32_e32 v178, v178
	v_rcp_f32_e32 v144, v144
	v_rcp_f32_e32 v179, v179
	v_rcp_f32_e32 v145, v145
	v_rcp_f32_e32 v180, v180
	v_rcp_f32_e32 v146, v146
	v_rcp_f32_e32 v181, v181
	v_rcp_f32_e32 v147, v147
	s_nop 0
	v_mul_f32_e32 v186, v178, v182
	v_mul_f32_e32 v187, v144, v152
	v_mul_f32_e32 v188, v179, v183
	v_mul_f32_e32 v189, v145, v153
	v_mul_f32_e32 v190, v180, v184
	v_mul_f32_e32 v191, v146, v154
	v_mul_f32_e32 v192, v181, v185
	v_mul_f32_e32 v193, v147, v155
	v_pk_mul_f32 v[108:109], v[108:109], v[186:187]
	v_pk_mul_f32 v[110:111], v[110:111], v[188:189]
	v_pk_mul_f32 v[104:105], v[104:105], v[190:191]
	v_pk_mul_f32 v[106:107], v[106:107], v[192:193]
	v_lshlrev_b32_e32 v178, 16, v148
	v_and_b32_e32 v148, 0xffff0000, v148
	v_lshlrev_b32_e32 v179, 16, v149
	v_and_b32_e32 v149, 0xffff0000, v149
	v_lshlrev_b32_e32 v180, 16, v150
	v_and_b32_e32 v150, 0xffff0000, v150
	v_lshlrev_b32_e32 v181, 16, v151
	v_and_b32_e32 v151, 0xffff0000, v151
	v_mul_f32_e32 v178, 0xbfb8aa3b, v178
	v_mul_f32_e32 v148, 0xbfb8aa3b, v148
	v_mul_f32_e32 v179, 0xbfb8aa3b, v179
	v_mul_f32_e32 v149, 0xbfb8aa3b, v149
	v_mul_f32_e32 v180, 0xbfb8aa3b, v180
	v_mul_f32_e32 v150, 0xbfb8aa3b, v150
	v_mul_f32_e32 v181, 0xbfb8aa3b, v181
	v_mul_f32_e32 v151, 0xbfb8aa3b, v151
	v_exp_f32_e32 v178, v178
	v_exp_f32_e32 v148, v148
	v_exp_f32_e32 v179, v179
	v_exp_f32_e32 v149, v149
	v_exp_f32_e32 v180, v180
	v_exp_f32_e32 v150, v150
	v_exp_f32_e32 v181, v181
	v_exp_f32_e32 v151, v151
	v_lshlrev_b32_e32 v182, 16, v156
	v_and_b32_e32 v156, 0xffff0000, v156
	v_lshlrev_b32_e32 v183, 16, v157
	v_and_b32_e32 v157, 0xffff0000, v157
	v_lshlrev_b32_e32 v184, 16, v158
	v_and_b32_e32 v158, 0xffff0000, v158
	v_lshlrev_b32_e32 v185, 16, v159
	v_and_b32_e32 v159, 0xffff0000, v159
	v_mul_f32_e32 v182, 0xbfb8aa3b, v182
	v_mul_f32_e32 v156, 0xbfb8aa3b, v156
	v_mul_f32_e32 v183, 0xbfb8aa3b, v183
	v_mul_f32_e32 v157, 0xbfb8aa3b, v157
	v_mul_f32_e32 v184, 0xbfb8aa3b, v184
	v_mul_f32_e32 v158, 0xbfb8aa3b, v158
	v_mul_f32_e32 v185, 0xbfb8aa3b, v185
	v_mul_f32_e32 v159, 0xbfb8aa3b, v159
	v_exp_f32_e32 v182, v182
	v_exp_f32_e32 v156, v156
	v_exp_f32_e32 v183, v183
	v_exp_f32_e32 v157, v157
	v_exp_f32_e32 v184, v184
	v_exp_f32_e32 v158, v158
	v_exp_f32_e32 v185, v185
	v_exp_f32_e32 v159, v159
	v_add_f32_e32 v178, 1.0, v178
	v_add_f32_e32 v148, 1.0, v148
	v_add_f32_e32 v179, 1.0, v179
	v_add_f32_e32 v149, 1.0, v149
	v_add_f32_e32 v180, 1.0, v180
	v_add_f32_e32 v150, 1.0, v150
	v_add_f32_e32 v181, 1.0, v181
	v_add_f32_e32 v151, 1.0, v151
	v_add_f32_e32 v182, 1.0, v182
	v_add_f32_e32 v156, 1.0, v156
	v_add_f32_e32 v183, 1.0, v183
	v_add_f32_e32 v157, 1.0, v157
	v_add_f32_e32 v184, 1.0, v184
	v_add_f32_e32 v158, 1.0, v158
	v_add_f32_e32 v185, 1.0, v185
	v_add_f32_e32 v159, 1.0, v159
	v_rcp_f32_e32 v178, v178
	v_rcp_f32_e32 v148, v148
	v_rcp_f32_e32 v179, v179
	v_rcp_f32_e32 v149, v149
	v_rcp_f32_e32 v180, v180
	v_rcp_f32_e32 v150, v150
	v_rcp_f32_e32 v181, v181
	v_rcp_f32_e32 v151, v151
	s_nop 0
	v_mul_f32_e32 v186, v178, v182
	v_mul_f32_e32 v187, v148, v156
	v_mul_f32_e32 v188, v179, v183
	v_mul_f32_e32 v189, v149, v157
	v_mul_f32_e32 v190, v180, v184
	v_mul_f32_e32 v191, v150, v158
	v_mul_f32_e32 v192, v181, v185
	v_mul_f32_e32 v193, v151, v159
	v_pk_mul_f32 v[76:77], v[76:77], v[186:187]
	v_pk_mul_f32 v[78:79], v[78:79], v[188:189]
	v_pk_mul_f32 v[72:73], v[72:73], v[190:191]
	v_pk_mul_f32 v[74:75], v[74:75], v[192:193]
	s_mov_b64 s[98:99], 0x1b0000
	v_lshl_add_u64 v[210:211], v[214:215], 0, s[98:99]
	global_load_dwordx4 v[144:147], v[210:211], off
	global_load_dwordx4 v[148:151], v[210:211], off offset:256
	global_load_dwordx4 v[152:155], v[210:211], off offset:2048
	global_load_dwordx4 v[156:159], v[210:211], off offset:2304
	s_waitcnt vmcnt(4)
	v_lshlrev_b32_e32 v178, 16, v160
	v_and_b32_e32 v160, 0xffff0000, v160
	v_lshlrev_b32_e32 v179, 16, v161
	v_and_b32_e32 v161, 0xffff0000, v161
	v_lshlrev_b32_e32 v180, 16, v162
	v_and_b32_e32 v162, 0xffff0000, v162
	v_lshlrev_b32_e32 v181, 16, v163
	v_and_b32_e32 v163, 0xffff0000, v163
	v_mul_f32_e32 v178, 0xbfb8aa3b, v178
	v_mul_f32_e32 v160, 0xbfb8aa3b, v160
	v_mul_f32_e32 v179, 0xbfb8aa3b, v179
	v_mul_f32_e32 v161, 0xbfb8aa3b, v161
	v_mul_f32_e32 v180, 0xbfb8aa3b, v180
	v_mul_f32_e32 v162, 0xbfb8aa3b, v162
	v_mul_f32_e32 v181, 0xbfb8aa3b, v181
	v_mul_f32_e32 v163, 0xbfb8aa3b, v163
	v_exp_f32_e32 v178, v178
	v_exp_f32_e32 v160, v160
	v_exp_f32_e32 v179, v179
	v_exp_f32_e32 v161, v161
	v_exp_f32_e32 v180, v180
	v_exp_f32_e32 v162, v162
	v_exp_f32_e32 v181, v181
	v_exp_f32_e32 v163, v163
	v_lshlrev_b32_e32 v182, 16, v170
	v_and_b32_e32 v170, 0xffff0000, v170
	v_lshlrev_b32_e32 v183, 16, v171
	v_and_b32_e32 v171, 0xffff0000, v171
	v_lshlrev_b32_e32 v184, 16, v172
	v_and_b32_e32 v172, 0xffff0000, v172
	v_lshlrev_b32_e32 v185, 16, v173
	v_and_b32_e32 v173, 0xffff0000, v173
	v_mul_f32_e32 v182, 0xbfb8aa3b, v182
	v_mul_f32_e32 v170, 0xbfb8aa3b, v170
	v_mul_f32_e32 v183, 0xbfb8aa3b, v183
	v_mul_f32_e32 v171, 0xbfb8aa3b, v171
	v_mul_f32_e32 v184, 0xbfb8aa3b, v184
	v_mul_f32_e32 v172, 0xbfb8aa3b, v172
	v_mul_f32_e32 v185, 0xbfb8aa3b, v185
	v_mul_f32_e32 v173, 0xbfb8aa3b, v173
	v_exp_f32_e32 v182, v182
	v_exp_f32_e32 v170, v170
	v_exp_f32_e32 v183, v183
	v_exp_f32_e32 v171, v171
	v_exp_f32_e32 v184, v184
	v_exp_f32_e32 v172, v172
	v_exp_f32_e32 v185, v185
	v_exp_f32_e32 v173, v173
	v_add_f32_e32 v178, 1.0, v178
	v_add_f32_e32 v160, 1.0, v160
	v_add_f32_e32 v179, 1.0, v179
	v_add_f32_e32 v161, 1.0, v161
	v_add_f32_e32 v180, 1.0, v180
	v_add_f32_e32 v162, 1.0, v162
	v_add_f32_e32 v181, 1.0, v181
	v_add_f32_e32 v163, 1.0, v163
	v_add_f32_e32 v182, 1.0, v182
	v_add_f32_e32 v170, 1.0, v170
	v_add_f32_e32 v183, 1.0, v183
	v_add_f32_e32 v171, 1.0, v171
	v_add_f32_e32 v184, 1.0, v184
	v_add_f32_e32 v172, 1.0, v172
	v_add_f32_e32 v185, 1.0, v185
	v_add_f32_e32 v173, 1.0, v173
	v_rcp_f32_e32 v178, v178
	v_rcp_f32_e32 v160, v160
	v_rcp_f32_e32 v179, v179
	v_rcp_f32_e32 v161, v161
	v_rcp_f32_e32 v180, v180
	v_rcp_f32_e32 v162, v162
	v_rcp_f32_e32 v181, v181
	v_rcp_f32_e32 v163, v163
	s_nop 0
	v_mul_f32_e32 v186, v178, v182
	v_mul_f32_e32 v187, v160, v170
	v_mul_f32_e32 v188, v179, v183
	v_mul_f32_e32 v189, v161, v171
	v_mul_f32_e32 v190, v180, v184
	v_mul_f32_e32 v191, v162, v172
	v_mul_f32_e32 v192, v181, v185
	v_mul_f32_e32 v193, v163, v173
	v_pk_mul_f32 v[100:101], v[100:101], v[186:187]
	v_pk_mul_f32 v[102:103], v[102:103], v[188:189]
	v_pk_mul_f32 v[96:97], v[96:97], v[190:191]
	v_pk_mul_f32 v[98:99], v[98:99], v[192:193]
	v_lshlrev_b32_e32 v178, 16, v164
	v_and_b32_e32 v164, 0xffff0000, v164
	v_lshlrev_b32_e32 v179, 16, v165
	v_and_b32_e32 v165, 0xffff0000, v165
	v_lshlrev_b32_e32 v180, 16, v166
	v_and_b32_e32 v166, 0xffff0000, v166
	v_lshlrev_b32_e32 v181, 16, v167
	v_and_b32_e32 v167, 0xffff0000, v167
	v_mul_f32_e32 v178, 0xbfb8aa3b, v178
	v_mul_f32_e32 v164, 0xbfb8aa3b, v164
	v_mul_f32_e32 v179, 0xbfb8aa3b, v179
	v_mul_f32_e32 v165, 0xbfb8aa3b, v165
	v_mul_f32_e32 v180, 0xbfb8aa3b, v180
	v_mul_f32_e32 v166, 0xbfb8aa3b, v166
	v_mul_f32_e32 v181, 0xbfb8aa3b, v181
	v_mul_f32_e32 v167, 0xbfb8aa3b, v167
	v_exp_f32_e32 v178, v178
	v_exp_f32_e32 v164, v164
	v_exp_f32_e32 v179, v179
	v_exp_f32_e32 v165, v165
	v_exp_f32_e32 v180, v180
	v_exp_f32_e32 v166, v166
	v_exp_f32_e32 v181, v181
	v_exp_f32_e32 v167, v167
	v_lshlrev_b32_e32 v182, 16, v174
	v_and_b32_e32 v174, 0xffff0000, v174
	v_lshlrev_b32_e32 v183, 16, v175
	v_and_b32_e32 v175, 0xffff0000, v175
	v_lshlrev_b32_e32 v184, 16, v176
	v_and_b32_e32 v176, 0xffff0000, v176
	v_lshlrev_b32_e32 v185, 16, v177
	v_and_b32_e32 v177, 0xffff0000, v177
	v_mul_f32_e32 v182, 0xbfb8aa3b, v182
	v_mul_f32_e32 v174, 0xbfb8aa3b, v174
	v_mul_f32_e32 v183, 0xbfb8aa3b, v183
	v_mul_f32_e32 v175, 0xbfb8aa3b, v175
	v_mul_f32_e32 v184, 0xbfb8aa3b, v184
	v_mul_f32_e32 v176, 0xbfb8aa3b, v176
	v_mul_f32_e32 v185, 0xbfb8aa3b, v185
	v_mul_f32_e32 v177, 0xbfb8aa3b, v177
	v_exp_f32_e32 v182, v182
	v_exp_f32_e32 v174, v174
	v_exp_f32_e32 v183, v183
	v_exp_f32_e32 v175, v175
	v_exp_f32_e32 v184, v184
	v_exp_f32_e32 v176, v176
	v_exp_f32_e32 v185, v185
	v_exp_f32_e32 v177, v177
	v_add_f32_e32 v178, 1.0, v178
	v_add_f32_e32 v164, 1.0, v164
	v_add_f32_e32 v179, 1.0, v179
	v_add_f32_e32 v165, 1.0, v165
	v_add_f32_e32 v180, 1.0, v180
	v_add_f32_e32 v166, 1.0, v166
	v_add_f32_e32 v181, 1.0, v181
	v_add_f32_e32 v167, 1.0, v167
	v_add_f32_e32 v182, 1.0, v182
	v_add_f32_e32 v174, 1.0, v174
	v_add_f32_e32 v183, 1.0, v183
	v_add_f32_e32 v175, 1.0, v175
	v_add_f32_e32 v184, 1.0, v184
	v_add_f32_e32 v176, 1.0, v176
	v_add_f32_e32 v185, 1.0, v185
	v_add_f32_e32 v177, 1.0, v177
	v_rcp_f32_e32 v178, v178
	v_rcp_f32_e32 v164, v164
	v_rcp_f32_e32 v179, v179
	v_rcp_f32_e32 v165, v165
	v_rcp_f32_e32 v180, v180
	v_rcp_f32_e32 v166, v166
	v_rcp_f32_e32 v181, v181
	v_rcp_f32_e32 v167, v167
	s_nop 0
	v_mul_f32_e32 v186, v178, v182
	v_mul_f32_e32 v187, v164, v174
	v_mul_f32_e32 v188, v179, v183
	v_mul_f32_e32 v189, v165, v175
	v_mul_f32_e32 v190, v180, v184
	v_mul_f32_e32 v191, v166, v176
	v_mul_f32_e32 v192, v181, v185
	v_mul_f32_e32 v193, v167, v177
	v_pk_mul_f32 v[68:69], v[68:69], v[186:187]
	v_pk_mul_f32 v[70:71], v[70:71], v[188:189]
	v_pk_mul_f32 v[64:65], v[64:65], v[190:191]
	v_pk_mul_f32 v[66:67], v[66:67], v[192:193]
	s_mov_b64 s[98:99], 0x1e6000
	v_lshl_add_u64 v[210:211], v[214:215], 0, s[98:99]
	global_load_dwordx4 v[160:163], v[210:211], off
	global_load_dwordx4 v[164:167], v[210:211], off offset:256
	global_load_dwordx4 v[170:173], v[210:211], off offset:2048
	global_load_dwordx4 v[174:177], v[210:211], off offset:2304
	s_waitcnt vmcnt(4)
	v_lshlrev_b32_e32 v178, 16, v144
	v_and_b32_e32 v144, 0xffff0000, v144
	v_lshlrev_b32_e32 v179, 16, v145
	v_and_b32_e32 v145, 0xffff0000, v145
	v_lshlrev_b32_e32 v180, 16, v146
	v_and_b32_e32 v146, 0xffff0000, v146
	v_lshlrev_b32_e32 v181, 16, v147
	v_and_b32_e32 v147, 0xffff0000, v147
	v_mul_f32_e32 v178, 0xbfb8aa3b, v178
	v_mul_f32_e32 v144, 0xbfb8aa3b, v144
	v_mul_f32_e32 v179, 0xbfb8aa3b, v179
	v_mul_f32_e32 v145, 0xbfb8aa3b, v145
	v_mul_f32_e32 v180, 0xbfb8aa3b, v180
	v_mul_f32_e32 v146, 0xbfb8aa3b, v146
	v_mul_f32_e32 v181, 0xbfb8aa3b, v181
	v_mul_f32_e32 v147, 0xbfb8aa3b, v147
	v_exp_f32_e32 v178, v178
	v_exp_f32_e32 v144, v144
	v_exp_f32_e32 v179, v179
	v_exp_f32_e32 v145, v145
	v_exp_f32_e32 v180, v180
	v_exp_f32_e32 v146, v146
	v_exp_f32_e32 v181, v181
	v_exp_f32_e32 v147, v147
	v_lshlrev_b32_e32 v182, 16, v152
	v_and_b32_e32 v152, 0xffff0000, v152
	v_lshlrev_b32_e32 v183, 16, v153
	v_and_b32_e32 v153, 0xffff0000, v153
	v_lshlrev_b32_e32 v184, 16, v154
	v_and_b32_e32 v154, 0xffff0000, v154
	v_lshlrev_b32_e32 v185, 16, v155
	v_and_b32_e32 v155, 0xffff0000, v155
	v_mul_f32_e32 v182, 0xbfb8aa3b, v182
	v_mul_f32_e32 v152, 0xbfb8aa3b, v152
	v_mul_f32_e32 v183, 0xbfb8aa3b, v183
	v_mul_f32_e32 v153, 0xbfb8aa3b, v153
	v_mul_f32_e32 v184, 0xbfb8aa3b, v184
	v_mul_f32_e32 v154, 0xbfb8aa3b, v154
	v_mul_f32_e32 v185, 0xbfb8aa3b, v185
	v_mul_f32_e32 v155, 0xbfb8aa3b, v155
	v_exp_f32_e32 v182, v182
	v_exp_f32_e32 v152, v152
	v_exp_f32_e32 v183, v183
	v_exp_f32_e32 v153, v153
	v_exp_f32_e32 v184, v184
	v_exp_f32_e32 v154, v154
	v_exp_f32_e32 v185, v185
	v_exp_f32_e32 v155, v155
	v_add_f32_e32 v178, 1.0, v178
	v_add_f32_e32 v144, 1.0, v144
	v_add_f32_e32 v179, 1.0, v179
	v_add_f32_e32 v145, 1.0, v145
	v_add_f32_e32 v180, 1.0, v180
	v_add_f32_e32 v146, 1.0, v146
	v_add_f32_e32 v181, 1.0, v181
	v_add_f32_e32 v147, 1.0, v147
	v_add_f32_e32 v182, 1.0, v182
	v_add_f32_e32 v152, 1.0, v152
	v_add_f32_e32 v183, 1.0, v183
	v_add_f32_e32 v153, 1.0, v153
	v_add_f32_e32 v184, 1.0, v184
	v_add_f32_e32 v154, 1.0, v154
	v_add_f32_e32 v185, 1.0, v185
	v_add_f32_e32 v155, 1.0, v155
	v_rcp_f32_e32 v178, v178
	v_rcp_f32_e32 v144, v144
	v_rcp_f32_e32 v179, v179
	v_rcp_f32_e32 v145, v145
	v_rcp_f32_e32 v180, v180
	v_rcp_f32_e32 v146, v146
	v_rcp_f32_e32 v181, v181
	v_rcp_f32_e32 v147, v147
	s_nop 0
	v_mul_f32_e32 v186, v178, v182
	v_mul_f32_e32 v187, v144, v152
	v_mul_f32_e32 v188, v179, v183
	v_mul_f32_e32 v189, v145, v153
	v_mul_f32_e32 v190, v180, v184
	v_mul_f32_e32 v191, v146, v154
	v_mul_f32_e32 v192, v181, v185
	v_mul_f32_e32 v193, v147, v155
	v_pk_mul_f32 v[60:61], v[60:61], v[186:187]
	v_pk_mul_f32 v[62:63], v[62:63], v[188:189]
	v_pk_mul_f32 v[56:57], v[56:57], v[190:191]
	v_pk_mul_f32 v[58:59], v[58:59], v[192:193]
	v_lshlrev_b32_e32 v178, 16, v148
	v_and_b32_e32 v148, 0xffff0000, v148
	v_lshlrev_b32_e32 v179, 16, v149
	v_and_b32_e32 v149, 0xffff0000, v149
	v_lshlrev_b32_e32 v180, 16, v150
	v_and_b32_e32 v150, 0xffff0000, v150
	v_lshlrev_b32_e32 v181, 16, v151
	v_and_b32_e32 v151, 0xffff0000, v151
	v_mul_f32_e32 v178, 0xbfb8aa3b, v178
	v_mul_f32_e32 v148, 0xbfb8aa3b, v148
	v_mul_f32_e32 v179, 0xbfb8aa3b, v179
	v_mul_f32_e32 v149, 0xbfb8aa3b, v149
	v_mul_f32_e32 v180, 0xbfb8aa3b, v180
	v_mul_f32_e32 v150, 0xbfb8aa3b, v150
	v_mul_f32_e32 v181, 0xbfb8aa3b, v181
	v_mul_f32_e32 v151, 0xbfb8aa3b, v151
	v_exp_f32_e32 v178, v178
	v_exp_f32_e32 v148, v148
	v_exp_f32_e32 v179, v179
	v_exp_f32_e32 v149, v149
	v_exp_f32_e32 v180, v180
	v_exp_f32_e32 v150, v150
	v_exp_f32_e32 v181, v181
	v_exp_f32_e32 v151, v151
	v_lshlrev_b32_e32 v182, 16, v156
	v_and_b32_e32 v156, 0xffff0000, v156
	v_lshlrev_b32_e32 v183, 16, v157
	v_and_b32_e32 v157, 0xffff0000, v157
	v_lshlrev_b32_e32 v184, 16, v158
	v_and_b32_e32 v158, 0xffff0000, v158
	v_lshlrev_b32_e32 v185, 16, v159
	v_and_b32_e32 v159, 0xffff0000, v159
	v_mul_f32_e32 v182, 0xbfb8aa3b, v182
	v_mul_f32_e32 v156, 0xbfb8aa3b, v156
	v_mul_f32_e32 v183, 0xbfb8aa3b, v183
	v_mul_f32_e32 v157, 0xbfb8aa3b, v157
	v_mul_f32_e32 v184, 0xbfb8aa3b, v184
	v_mul_f32_e32 v158, 0xbfb8aa3b, v158
	v_mul_f32_e32 v185, 0xbfb8aa3b, v185
	v_mul_f32_e32 v159, 0xbfb8aa3b, v159
	v_exp_f32_e32 v182, v182
	v_exp_f32_e32 v156, v156
	v_exp_f32_e32 v183, v183
	v_exp_f32_e32 v157, v157
	v_exp_f32_e32 v184, v184
	v_exp_f32_e32 v158, v158
	v_exp_f32_e32 v185, v185
	v_exp_f32_e32 v159, v159
	v_add_f32_e32 v178, 1.0, v178
	v_add_f32_e32 v148, 1.0, v148
	v_add_f32_e32 v179, 1.0, v179
	v_add_f32_e32 v149, 1.0, v149
	v_add_f32_e32 v180, 1.0, v180
	v_add_f32_e32 v150, 1.0, v150
	v_add_f32_e32 v181, 1.0, v181
	v_add_f32_e32 v151, 1.0, v151
	v_add_f32_e32 v182, 1.0, v182
	v_add_f32_e32 v156, 1.0, v156
	v_add_f32_e32 v183, 1.0, v183
	v_add_f32_e32 v157, 1.0, v157
	v_add_f32_e32 v184, 1.0, v184
	v_add_f32_e32 v158, 1.0, v158
	v_add_f32_e32 v185, 1.0, v185
	v_add_f32_e32 v159, 1.0, v159
	v_rcp_f32_e32 v178, v178
	v_rcp_f32_e32 v148, v148
	v_rcp_f32_e32 v179, v179
	v_rcp_f32_e32 v149, v149
	v_rcp_f32_e32 v180, v180
	v_rcp_f32_e32 v150, v150
	v_rcp_f32_e32 v181, v181
	v_rcp_f32_e32 v151, v151
	s_nop 0
	v_mul_f32_e32 v186, v178, v182
	v_mul_f32_e32 v187, v148, v156
	v_mul_f32_e32 v188, v179, v183
	v_mul_f32_e32 v189, v149, v157
	v_mul_f32_e32 v190, v180, v184
	v_mul_f32_e32 v191, v150, v158
	v_mul_f32_e32 v192, v181, v185
	v_mul_f32_e32 v193, v151, v159
	v_pk_mul_f32 v[28:29], v[28:29], v[186:187]
	v_pk_mul_f32 v[30:31], v[30:31], v[188:189]
	v_pk_mul_f32 v[24:25], v[24:25], v[190:191]
	v_pk_mul_f32 v[26:27], v[26:27], v[192:193]
	s_mov_b64 s[98:99], 0x21c000
	v_lshl_add_u64 v[210:211], v[214:215], 0, s[98:99]
	global_load_dwordx4 v[144:147], v[210:211], off
	global_load_dwordx4 v[148:151], v[210:211], off offset:256
	global_load_dwordx4 v[152:155], v[210:211], off offset:2048
	global_load_dwordx4 v[156:159], v[210:211], off offset:2304
	s_waitcnt vmcnt(4)
	v_lshlrev_b32_e32 v178, 16, v160
	v_and_b32_e32 v160, 0xffff0000, v160
	v_lshlrev_b32_e32 v179, 16, v161
	v_and_b32_e32 v161, 0xffff0000, v161
	v_lshlrev_b32_e32 v180, 16, v162
	v_and_b32_e32 v162, 0xffff0000, v162
	v_lshlrev_b32_e32 v181, 16, v163
	v_and_b32_e32 v163, 0xffff0000, v163
	v_mul_f32_e32 v178, 0xbfb8aa3b, v178
	v_mul_f32_e32 v160, 0xbfb8aa3b, v160
	v_mul_f32_e32 v179, 0xbfb8aa3b, v179
	v_mul_f32_e32 v161, 0xbfb8aa3b, v161
	v_mul_f32_e32 v180, 0xbfb8aa3b, v180
	v_mul_f32_e32 v162, 0xbfb8aa3b, v162
	v_mul_f32_e32 v181, 0xbfb8aa3b, v181
	v_mul_f32_e32 v163, 0xbfb8aa3b, v163
	v_exp_f32_e32 v178, v178
	v_exp_f32_e32 v160, v160
	v_exp_f32_e32 v179, v179
	v_exp_f32_e32 v161, v161
	v_exp_f32_e32 v180, v180
	v_exp_f32_e32 v162, v162
	v_exp_f32_e32 v181, v181
	v_exp_f32_e32 v163, v163
	v_lshlrev_b32_e32 v182, 16, v170
	v_and_b32_e32 v170, 0xffff0000, v170
	v_lshlrev_b32_e32 v183, 16, v171
	v_and_b32_e32 v171, 0xffff0000, v171
	v_lshlrev_b32_e32 v184, 16, v172
	v_and_b32_e32 v172, 0xffff0000, v172
	v_lshlrev_b32_e32 v185, 16, v173
	v_and_b32_e32 v173, 0xffff0000, v173
	v_mul_f32_e32 v182, 0xbfb8aa3b, v182
	v_mul_f32_e32 v170, 0xbfb8aa3b, v170
	v_mul_f32_e32 v183, 0xbfb8aa3b, v183
	v_mul_f32_e32 v171, 0xbfb8aa3b, v171
	v_mul_f32_e32 v184, 0xbfb8aa3b, v184
	v_mul_f32_e32 v172, 0xbfb8aa3b, v172
	v_mul_f32_e32 v185, 0xbfb8aa3b, v185
	v_mul_f32_e32 v173, 0xbfb8aa3b, v173
	v_exp_f32_e32 v182, v182
	v_exp_f32_e32 v170, v170
	v_exp_f32_e32 v183, v183
	v_exp_f32_e32 v171, v171
	v_exp_f32_e32 v184, v184
	v_exp_f32_e32 v172, v172
	v_exp_f32_e32 v185, v185
	v_exp_f32_e32 v173, v173
	v_add_f32_e32 v178, 1.0, v178
	v_add_f32_e32 v160, 1.0, v160
	v_add_f32_e32 v179, 1.0, v179
	v_add_f32_e32 v161, 1.0, v161
	v_add_f32_e32 v180, 1.0, v180
	v_add_f32_e32 v162, 1.0, v162
	v_add_f32_e32 v181, 1.0, v181
	v_add_f32_e32 v163, 1.0, v163
	v_add_f32_e32 v182, 1.0, v182
	v_add_f32_e32 v170, 1.0, v170
	v_add_f32_e32 v183, 1.0, v183
	v_add_f32_e32 v171, 1.0, v171
	v_add_f32_e32 v184, 1.0, v184
	v_add_f32_e32 v172, 1.0, v172
	v_add_f32_e32 v185, 1.0, v185
	v_add_f32_e32 v173, 1.0, v173
	v_rcp_f32_e32 v178, v178
	v_rcp_f32_e32 v160, v160
	v_rcp_f32_e32 v179, v179
	v_rcp_f32_e32 v161, v161
	v_rcp_f32_e32 v180, v180
	v_rcp_f32_e32 v162, v162
	v_rcp_f32_e32 v181, v181
	v_rcp_f32_e32 v163, v163
	s_nop 0
	v_mul_f32_e32 v186, v178, v182
	v_mul_f32_e32 v187, v160, v170
	v_mul_f32_e32 v188, v179, v183
	v_mul_f32_e32 v189, v161, v171
	v_mul_f32_e32 v190, v180, v184
	v_mul_f32_e32 v191, v162, v172
	v_mul_f32_e32 v192, v181, v185
	v_mul_f32_e32 v193, v163, v173
	v_pk_mul_f32 v[52:53], v[52:53], v[186:187]
	v_pk_mul_f32 v[54:55], v[54:55], v[188:189]
	v_pk_mul_f32 v[48:49], v[48:49], v[190:191]
	v_pk_mul_f32 v[50:51], v[50:51], v[192:193]
	v_lshlrev_b32_e32 v178, 16, v164
	v_and_b32_e32 v164, 0xffff0000, v164
	v_lshlrev_b32_e32 v179, 16, v165
	v_and_b32_e32 v165, 0xffff0000, v165
	v_lshlrev_b32_e32 v180, 16, v166
	v_and_b32_e32 v166, 0xffff0000, v166
	v_lshlrev_b32_e32 v181, 16, v167
	v_and_b32_e32 v167, 0xffff0000, v167
	v_mul_f32_e32 v178, 0xbfb8aa3b, v178
	v_mul_f32_e32 v164, 0xbfb8aa3b, v164
	v_mul_f32_e32 v179, 0xbfb8aa3b, v179
	v_mul_f32_e32 v165, 0xbfb8aa3b, v165
	v_mul_f32_e32 v180, 0xbfb8aa3b, v180
	v_mul_f32_e32 v166, 0xbfb8aa3b, v166
	v_mul_f32_e32 v181, 0xbfb8aa3b, v181
	v_mul_f32_e32 v167, 0xbfb8aa3b, v167
	v_exp_f32_e32 v178, v178
	v_exp_f32_e32 v164, v164
	v_exp_f32_e32 v179, v179
	v_exp_f32_e32 v165, v165
	v_exp_f32_e32 v180, v180
	v_exp_f32_e32 v166, v166
	v_exp_f32_e32 v181, v181
	v_exp_f32_e32 v167, v167
	v_lshlrev_b32_e32 v182, 16, v174
	v_and_b32_e32 v174, 0xffff0000, v174
	v_lshlrev_b32_e32 v183, 16, v175
	v_and_b32_e32 v175, 0xffff0000, v175
	v_lshlrev_b32_e32 v184, 16, v176
	v_and_b32_e32 v176, 0xffff0000, v176
	v_lshlrev_b32_e32 v185, 16, v177
	v_and_b32_e32 v177, 0xffff0000, v177
	v_mul_f32_e32 v182, 0xbfb8aa3b, v182
	v_mul_f32_e32 v174, 0xbfb8aa3b, v174
	v_mul_f32_e32 v183, 0xbfb8aa3b, v183
	v_mul_f32_e32 v175, 0xbfb8aa3b, v175
	v_mul_f32_e32 v184, 0xbfb8aa3b, v184
	v_mul_f32_e32 v176, 0xbfb8aa3b, v176
	v_mul_f32_e32 v185, 0xbfb8aa3b, v185
	v_mul_f32_e32 v177, 0xbfb8aa3b, v177
	v_exp_f32_e32 v182, v182
	v_exp_f32_e32 v174, v174
	v_exp_f32_e32 v183, v183
	v_exp_f32_e32 v175, v175
	v_exp_f32_e32 v184, v184
	v_exp_f32_e32 v176, v176
	v_exp_f32_e32 v185, v185
	v_exp_f32_e32 v177, v177
	v_add_f32_e32 v178, 1.0, v178
	v_add_f32_e32 v164, 1.0, v164
	v_add_f32_e32 v179, 1.0, v179
	v_add_f32_e32 v165, 1.0, v165
	v_add_f32_e32 v180, 1.0, v180
	v_add_f32_e32 v166, 1.0, v166
	v_add_f32_e32 v181, 1.0, v181
	v_add_f32_e32 v167, 1.0, v167
	v_add_f32_e32 v182, 1.0, v182
	v_add_f32_e32 v174, 1.0, v174
	v_add_f32_e32 v183, 1.0, v183
	v_add_f32_e32 v175, 1.0, v175
	v_add_f32_e32 v184, 1.0, v184
	v_add_f32_e32 v176, 1.0, v176
	v_add_f32_e32 v185, 1.0, v185
	v_add_f32_e32 v177, 1.0, v177
	v_rcp_f32_e32 v178, v178
	v_rcp_f32_e32 v164, v164
	v_rcp_f32_e32 v179, v179
	v_rcp_f32_e32 v165, v165
	v_rcp_f32_e32 v180, v180
	v_rcp_f32_e32 v166, v166
	v_rcp_f32_e32 v181, v181
	v_rcp_f32_e32 v167, v167
	s_nop 0
	v_mul_f32_e32 v186, v178, v182
	v_mul_f32_e32 v187, v164, v174
	v_mul_f32_e32 v188, v179, v183
	v_mul_f32_e32 v189, v165, v175
	v_mul_f32_e32 v190, v180, v184
	v_mul_f32_e32 v191, v166, v176
	v_mul_f32_e32 v192, v181, v185
	v_mul_f32_e32 v193, v167, v177
	v_pk_mul_f32 v[20:21], v[20:21], v[186:187]
	v_pk_mul_f32 v[22:23], v[22:23], v[188:189]
	v_pk_mul_f32 v[16:17], v[16:17], v[190:191]
	v_pk_mul_f32 v[18:19], v[18:19], v[192:193]
	s_mov_b64 s[98:99], 0x252000
	v_lshl_add_u64 v[210:211], v[214:215], 0, s[98:99]
	global_load_dwordx4 v[160:163], v[210:211], off
	global_load_dwordx4 v[164:167], v[210:211], off offset:256
	global_load_dwordx4 v[170:173], v[210:211], off offset:2048
	global_load_dwordx4 v[174:177], v[210:211], off offset:2304
	s_waitcnt vmcnt(4)
	v_lshlrev_b32_e32 v178, 16, v144
	v_and_b32_e32 v144, 0xffff0000, v144
	v_lshlrev_b32_e32 v179, 16, v145
	v_and_b32_e32 v145, 0xffff0000, v145
	v_lshlrev_b32_e32 v180, 16, v146
	v_and_b32_e32 v146, 0xffff0000, v146
	v_lshlrev_b32_e32 v181, 16, v147
	v_and_b32_e32 v147, 0xffff0000, v147
	v_mul_f32_e32 v178, 0xbfb8aa3b, v178
	v_mul_f32_e32 v144, 0xbfb8aa3b, v144
	v_mul_f32_e32 v179, 0xbfb8aa3b, v179
	v_mul_f32_e32 v145, 0xbfb8aa3b, v145
	v_mul_f32_e32 v180, 0xbfb8aa3b, v180
	v_mul_f32_e32 v146, 0xbfb8aa3b, v146
	v_mul_f32_e32 v181, 0xbfb8aa3b, v181
	v_mul_f32_e32 v147, 0xbfb8aa3b, v147
	v_exp_f32_e32 v178, v178
	v_exp_f32_e32 v144, v144
	v_exp_f32_e32 v179, v179
	v_exp_f32_e32 v145, v145
	v_exp_f32_e32 v180, v180
	v_exp_f32_e32 v146, v146
	v_exp_f32_e32 v181, v181
	v_exp_f32_e32 v147, v147
	v_lshlrev_b32_e32 v182, 16, v152
	v_and_b32_e32 v152, 0xffff0000, v152
	v_lshlrev_b32_e32 v183, 16, v153
	v_and_b32_e32 v153, 0xffff0000, v153
	v_lshlrev_b32_e32 v184, 16, v154
	v_and_b32_e32 v154, 0xffff0000, v154
	v_lshlrev_b32_e32 v185, 16, v155
	v_and_b32_e32 v155, 0xffff0000, v155
	v_mul_f32_e32 v182, 0xbfb8aa3b, v182
	v_mul_f32_e32 v152, 0xbfb8aa3b, v152
	v_mul_f32_e32 v183, 0xbfb8aa3b, v183
	v_mul_f32_e32 v153, 0xbfb8aa3b, v153
	v_mul_f32_e32 v184, 0xbfb8aa3b, v184
	v_mul_f32_e32 v154, 0xbfb8aa3b, v154
	v_mul_f32_e32 v185, 0xbfb8aa3b, v185
	v_mul_f32_e32 v155, 0xbfb8aa3b, v155
	v_exp_f32_e32 v182, v182
	v_exp_f32_e32 v152, v152
	v_exp_f32_e32 v183, v183
	v_exp_f32_e32 v153, v153
	v_exp_f32_e32 v184, v184
	v_exp_f32_e32 v154, v154
	v_exp_f32_e32 v185, v185
	v_exp_f32_e32 v155, v155
	v_add_f32_e32 v178, 1.0, v178
	v_add_f32_e32 v144, 1.0, v144
	v_add_f32_e32 v179, 1.0, v179
	v_add_f32_e32 v145, 1.0, v145
	v_add_f32_e32 v180, 1.0, v180
	v_add_f32_e32 v146, 1.0, v146
	v_add_f32_e32 v181, 1.0, v181
	v_add_f32_e32 v147, 1.0, v147
	v_add_f32_e32 v182, 1.0, v182
	v_add_f32_e32 v152, 1.0, v152
	v_add_f32_e32 v183, 1.0, v183
	v_add_f32_e32 v153, 1.0, v153
	v_add_f32_e32 v184, 1.0, v184
	v_add_f32_e32 v154, 1.0, v154
	v_add_f32_e32 v185, 1.0, v185
	v_add_f32_e32 v155, 1.0, v155
	v_rcp_f32_e32 v178, v178
	v_rcp_f32_e32 v144, v144
	v_rcp_f32_e32 v179, v179
	v_rcp_f32_e32 v145, v145
	v_rcp_f32_e32 v180, v180
	v_rcp_f32_e32 v146, v146
	v_rcp_f32_e32 v181, v181
	v_rcp_f32_e32 v147, v147
	s_nop 0
	v_mul_f32_e32 v186, v178, v182
	v_mul_f32_e32 v187, v144, v152
	v_mul_f32_e32 v188, v179, v183
	v_mul_f32_e32 v189, v145, v153
	v_mul_f32_e32 v190, v180, v184
	v_mul_f32_e32 v191, v146, v154
	v_mul_f32_e32 v192, v181, v185
	v_mul_f32_e32 v193, v147, v155
	v_pk_mul_f32 v[44:45], v[44:45], v[186:187]
	v_pk_mul_f32 v[46:47], v[46:47], v[188:189]
	v_pk_mul_f32 v[40:41], v[40:41], v[190:191]
	v_pk_mul_f32 v[42:43], v[42:43], v[192:193]
	v_lshlrev_b32_e32 v178, 16, v148
	v_and_b32_e32 v148, 0xffff0000, v148
	v_lshlrev_b32_e32 v179, 16, v149
	v_and_b32_e32 v149, 0xffff0000, v149
	v_lshlrev_b32_e32 v180, 16, v150
	v_and_b32_e32 v150, 0xffff0000, v150
	v_lshlrev_b32_e32 v181, 16, v151
	v_and_b32_e32 v151, 0xffff0000, v151
	v_mul_f32_e32 v178, 0xbfb8aa3b, v178
	v_mul_f32_e32 v148, 0xbfb8aa3b, v148
	v_mul_f32_e32 v179, 0xbfb8aa3b, v179
	v_mul_f32_e32 v149, 0xbfb8aa3b, v149
	v_mul_f32_e32 v180, 0xbfb8aa3b, v180
	v_mul_f32_e32 v150, 0xbfb8aa3b, v150
	v_mul_f32_e32 v181, 0xbfb8aa3b, v181
	v_mul_f32_e32 v151, 0xbfb8aa3b, v151
	v_exp_f32_e32 v178, v178
	v_exp_f32_e32 v148, v148
	v_exp_f32_e32 v179, v179
	v_exp_f32_e32 v149, v149
	v_exp_f32_e32 v180, v180
	v_exp_f32_e32 v150, v150
	v_exp_f32_e32 v181, v181
	v_exp_f32_e32 v151, v151
	v_lshlrev_b32_e32 v182, 16, v156
	v_and_b32_e32 v156, 0xffff0000, v156
	v_lshlrev_b32_e32 v183, 16, v157
	v_and_b32_e32 v157, 0xffff0000, v157
	v_lshlrev_b32_e32 v184, 16, v158
	v_and_b32_e32 v158, 0xffff0000, v158
	v_lshlrev_b32_e32 v185, 16, v159
	v_and_b32_e32 v159, 0xffff0000, v159
	v_mul_f32_e32 v182, 0xbfb8aa3b, v182
	v_mul_f32_e32 v156, 0xbfb8aa3b, v156
	v_mul_f32_e32 v183, 0xbfb8aa3b, v183
	v_mul_f32_e32 v157, 0xbfb8aa3b, v157
	v_mul_f32_e32 v184, 0xbfb8aa3b, v184
	v_mul_f32_e32 v158, 0xbfb8aa3b, v158
	v_mul_f32_e32 v185, 0xbfb8aa3b, v185
	v_mul_f32_e32 v159, 0xbfb8aa3b, v159
	v_exp_f32_e32 v182, v182
	v_exp_f32_e32 v156, v156
	v_exp_f32_e32 v183, v183
	v_exp_f32_e32 v157, v157
	v_exp_f32_e32 v184, v184
	v_exp_f32_e32 v158, v158
	v_exp_f32_e32 v185, v185
	v_exp_f32_e32 v159, v159
	v_add_f32_e32 v178, 1.0, v178
	v_add_f32_e32 v148, 1.0, v148
	v_add_f32_e32 v179, 1.0, v179
	v_add_f32_e32 v149, 1.0, v149
	v_add_f32_e32 v180, 1.0, v180
	v_add_f32_e32 v150, 1.0, v150
	v_add_f32_e32 v181, 1.0, v181
	v_add_f32_e32 v151, 1.0, v151
	v_add_f32_e32 v182, 1.0, v182
	v_add_f32_e32 v156, 1.0, v156
	v_add_f32_e32 v183, 1.0, v183
	v_add_f32_e32 v157, 1.0, v157
	v_add_f32_e32 v184, 1.0, v184
	v_add_f32_e32 v158, 1.0, v158
	v_add_f32_e32 v185, 1.0, v185
	v_add_f32_e32 v159, 1.0, v159
	v_rcp_f32_e32 v178, v178
	v_rcp_f32_e32 v148, v148
	v_rcp_f32_e32 v179, v179
	v_rcp_f32_e32 v149, v149
	v_rcp_f32_e32 v180, v180
	v_rcp_f32_e32 v150, v150
	v_rcp_f32_e32 v181, v181
	v_rcp_f32_e32 v151, v151
	s_nop 0
	v_mul_f32_e32 v186, v178, v182
	v_mul_f32_e32 v187, v148, v156
	v_mul_f32_e32 v188, v179, v183
	v_mul_f32_e32 v189, v149, v157
	v_mul_f32_e32 v190, v180, v184
	v_mul_f32_e32 v191, v150, v158
	v_mul_f32_e32 v192, v181, v185
	v_mul_f32_e32 v193, v151, v159
	v_pk_mul_f32 v[12:13], v[12:13], v[186:187]
	v_pk_mul_f32 v[14:15], v[14:15], v[188:189]
	v_pk_mul_f32 v[8:9], v[8:9], v[190:191]
	v_pk_mul_f32 v[10:11], v[10:11], v[192:193]
	s_waitcnt vmcnt(0)
	v_lshlrev_b32_e32 v178, 16, v160
	v_and_b32_e32 v160, 0xffff0000, v160
	v_lshlrev_b32_e32 v179, 16, v161
	v_and_b32_e32 v161, 0xffff0000, v161
	v_lshlrev_b32_e32 v180, 16, v162
	v_and_b32_e32 v162, 0xffff0000, v162
	v_lshlrev_b32_e32 v181, 16, v163
	v_and_b32_e32 v163, 0xffff0000, v163
	v_mul_f32_e32 v178, 0xbfb8aa3b, v178
	v_mul_f32_e32 v160, 0xbfb8aa3b, v160
	v_mul_f32_e32 v179, 0xbfb8aa3b, v179
	v_mul_f32_e32 v161, 0xbfb8aa3b, v161
	v_mul_f32_e32 v180, 0xbfb8aa3b, v180
	v_mul_f32_e32 v162, 0xbfb8aa3b, v162
	v_mul_f32_e32 v181, 0xbfb8aa3b, v181
	v_mul_f32_e32 v163, 0xbfb8aa3b, v163
	v_exp_f32_e32 v178, v178
	v_exp_f32_e32 v160, v160
	v_exp_f32_e32 v179, v179
	v_exp_f32_e32 v161, v161
	v_exp_f32_e32 v180, v180
	v_exp_f32_e32 v162, v162
	v_exp_f32_e32 v181, v181
	v_exp_f32_e32 v163, v163
	v_lshlrev_b32_e32 v182, 16, v170
	v_and_b32_e32 v170, 0xffff0000, v170
	v_lshlrev_b32_e32 v183, 16, v171
	v_and_b32_e32 v171, 0xffff0000, v171
	v_lshlrev_b32_e32 v184, 16, v172
	v_and_b32_e32 v172, 0xffff0000, v172
	v_lshlrev_b32_e32 v185, 16, v173
	v_and_b32_e32 v173, 0xffff0000, v173
	v_mul_f32_e32 v182, 0xbfb8aa3b, v182
	v_mul_f32_e32 v170, 0xbfb8aa3b, v170
	v_mul_f32_e32 v183, 0xbfb8aa3b, v183
	v_mul_f32_e32 v171, 0xbfb8aa3b, v171
	v_mul_f32_e32 v184, 0xbfb8aa3b, v184
	v_mul_f32_e32 v172, 0xbfb8aa3b, v172
	v_mul_f32_e32 v185, 0xbfb8aa3b, v185
	v_mul_f32_e32 v173, 0xbfb8aa3b, v173
	v_exp_f32_e32 v182, v182
	v_exp_f32_e32 v170, v170
	v_exp_f32_e32 v183, v183
	v_exp_f32_e32 v171, v171
	v_exp_f32_e32 v184, v184
	v_exp_f32_e32 v172, v172
	v_exp_f32_e32 v185, v185
	v_exp_f32_e32 v173, v173
	v_add_f32_e32 v178, 1.0, v178
	v_add_f32_e32 v160, 1.0, v160
	v_add_f32_e32 v179, 1.0, v179
	v_add_f32_e32 v161, 1.0, v161
	v_add_f32_e32 v180, 1.0, v180
	v_add_f32_e32 v162, 1.0, v162
	v_add_f32_e32 v181, 1.0, v181
	v_add_f32_e32 v163, 1.0, v163
	v_add_f32_e32 v182, 1.0, v182
	v_add_f32_e32 v170, 1.0, v170
	v_add_f32_e32 v183, 1.0, v183
	v_add_f32_e32 v171, 1.0, v171
	v_add_f32_e32 v184, 1.0, v184
	v_add_f32_e32 v172, 1.0, v172
	v_add_f32_e32 v185, 1.0, v185
	v_add_f32_e32 v173, 1.0, v173
	v_rcp_f32_e32 v178, v178
	v_rcp_f32_e32 v160, v160
	v_rcp_f32_e32 v179, v179
	v_rcp_f32_e32 v161, v161
	v_rcp_f32_e32 v180, v180
	v_rcp_f32_e32 v162, v162
	v_rcp_f32_e32 v181, v181
	v_rcp_f32_e32 v163, v163
	s_nop 0
	v_mul_f32_e32 v186, v178, v182
	v_mul_f32_e32 v187, v160, v170
	v_mul_f32_e32 v188, v179, v183
	v_mul_f32_e32 v189, v161, v171
	v_mul_f32_e32 v190, v180, v184
	v_mul_f32_e32 v191, v162, v172
	v_mul_f32_e32 v192, v181, v185
	v_mul_f32_e32 v193, v163, v173
	v_pk_mul_f32 v[36:37], v[36:37], v[186:187]
	v_pk_mul_f32 v[38:39], v[38:39], v[188:189]
	v_pk_mul_f32 v[32:33], v[32:33], v[190:191]
	v_pk_mul_f32 v[34:35], v[34:35], v[192:193]
	v_lshlrev_b32_e32 v178, 16, v164
	v_and_b32_e32 v164, 0xffff0000, v164
	v_lshlrev_b32_e32 v179, 16, v165
	v_and_b32_e32 v165, 0xffff0000, v165
	v_lshlrev_b32_e32 v180, 16, v166
	v_and_b32_e32 v166, 0xffff0000, v166
	v_lshlrev_b32_e32 v181, 16, v167
	v_and_b32_e32 v167, 0xffff0000, v167
	v_mul_f32_e32 v178, 0xbfb8aa3b, v178
	v_mul_f32_e32 v164, 0xbfb8aa3b, v164
	v_mul_f32_e32 v179, 0xbfb8aa3b, v179
	v_mul_f32_e32 v165, 0xbfb8aa3b, v165
	v_mul_f32_e32 v180, 0xbfb8aa3b, v180
	v_mul_f32_e32 v166, 0xbfb8aa3b, v166
	v_mul_f32_e32 v181, 0xbfb8aa3b, v181
	v_mul_f32_e32 v167, 0xbfb8aa3b, v167
	v_exp_f32_e32 v178, v178
	v_exp_f32_e32 v164, v164
	v_exp_f32_e32 v179, v179
	v_exp_f32_e32 v165, v165
	v_exp_f32_e32 v180, v180
	v_exp_f32_e32 v166, v166
	v_exp_f32_e32 v181, v181
	v_exp_f32_e32 v167, v167
	v_lshlrev_b32_e32 v182, 16, v174
	v_and_b32_e32 v174, 0xffff0000, v174
	v_lshlrev_b32_e32 v183, 16, v175
	v_and_b32_e32 v175, 0xffff0000, v175
	v_lshlrev_b32_e32 v184, 16, v176
	v_and_b32_e32 v176, 0xffff0000, v176
	v_lshlrev_b32_e32 v185, 16, v177
	v_and_b32_e32 v177, 0xffff0000, v177
	v_mul_f32_e32 v182, 0xbfb8aa3b, v182
	v_mul_f32_e32 v174, 0xbfb8aa3b, v174
	v_mul_f32_e32 v183, 0xbfb8aa3b, v183
	v_mul_f32_e32 v175, 0xbfb8aa3b, v175
	v_mul_f32_e32 v184, 0xbfb8aa3b, v184
	v_mul_f32_e32 v176, 0xbfb8aa3b, v176
	v_mul_f32_e32 v185, 0xbfb8aa3b, v185
	v_mul_f32_e32 v177, 0xbfb8aa3b, v177
	v_exp_f32_e32 v182, v182
	v_exp_f32_e32 v174, v174
	v_exp_f32_e32 v183, v183
	v_exp_f32_e32 v175, v175
	v_exp_f32_e32 v184, v184
	v_exp_f32_e32 v176, v176
	v_exp_f32_e32 v185, v185
	v_exp_f32_e32 v177, v177
	v_add_f32_e32 v178, 1.0, v178
	v_add_f32_e32 v164, 1.0, v164
	v_add_f32_e32 v179, 1.0, v179
	v_add_f32_e32 v165, 1.0, v165
	v_add_f32_e32 v180, 1.0, v180
	v_add_f32_e32 v166, 1.0, v166
	v_add_f32_e32 v181, 1.0, v181
	v_add_f32_e32 v167, 1.0, v167
	v_add_f32_e32 v182, 1.0, v182
	v_add_f32_e32 v174, 1.0, v174
	v_add_f32_e32 v183, 1.0, v183
	v_add_f32_e32 v175, 1.0, v175
	v_add_f32_e32 v184, 1.0, v184
	v_add_f32_e32 v176, 1.0, v176
	v_add_f32_e32 v185, 1.0, v185
	v_add_f32_e32 v177, 1.0, v177
	v_rcp_f32_e32 v178, v178
	v_rcp_f32_e32 v164, v164
	v_rcp_f32_e32 v179, v179
	v_rcp_f32_e32 v165, v165
	v_rcp_f32_e32 v180, v180
	v_rcp_f32_e32 v166, v166
	v_rcp_f32_e32 v181, v181
	v_rcp_f32_e32 v167, v167
	s_nop 0
	v_mul_f32_e32 v186, v178, v182
	v_mul_f32_e32 v187, v164, v174
	v_mul_f32_e32 v188, v179, v183
	v_mul_f32_e32 v189, v165, v175
	v_mul_f32_e32 v190, v180, v184
	v_mul_f32_e32 v191, v166, v176
	v_mul_f32_e32 v192, v181, v185
	v_mul_f32_e32 v193, v167, v177
	v_pk_mul_f32 v[4:5], v[4:5], v[186:187]
	v_pk_mul_f32 v[6:7], v[6:7], v[188:189]
	v_pk_mul_f32 v[0:1], v[0:1], v[190:191]
	v_pk_mul_f32 v[2:3], v[2:3], v[192:193]
	s_branch .Lmgepi_done
.Lmgepi_last:
	v_mov_b64_e32 v[210:211], v[214:215]
	global_load_dwordx4 v[144:147], v[210:211], off
	global_load_dwordx4 v[148:151], v[210:211], off offset:256
	s_mov_b64 s[98:99], 0x36000
	v_lshl_add_u64 v[210:211], v[214:215], 0, s[98:99]
	global_load_dwordx4 v[152:155], v[210:211], off
	global_load_dwordx4 v[156:159], v[210:211], off offset:256
	s_waitcnt vmcnt(2)
	v_mov_b64_e32 v[210:211], v[216:217]
	v_lshlrev_b32_e32 v178, 16, v144
	v_and_b32_e32 v144, 0xffff0000, v144
	v_lshlrev_b32_e32 v179, 16, v145
	v_and_b32_e32 v145, 0xffff0000, v145
	v_lshlrev_b32_e32 v180, 16, v146
	v_and_b32_e32 v146, 0xffff0000, v146
	v_lshlrev_b32_e32 v181, 16, v147
	v_and_b32_e32 v147, 0xffff0000, v147
	v_mul_f32_e32 v178, 0xbfb8aa3b, v178
	v_mul_f32_e32 v144, 0xbfb8aa3b, v144
	v_mul_f32_e32 v179, 0xbfb8aa3b, v179
	v_mul_f32_e32 v145, 0xbfb8aa3b, v145
	v_mul_f32_e32 v180, 0xbfb8aa3b, v180
	v_mul_f32_e32 v146, 0xbfb8aa3b, v146
	v_mul_f32_e32 v181, 0xbfb8aa3b, v181
	v_mul_f32_e32 v147, 0xbfb8aa3b, v147
	v_exp_f32_e32 v178, v178
	v_exp_f32_e32 v144, v144
	v_exp_f32_e32 v179, v179
	v_exp_f32_e32 v145, v145
	v_exp_f32_e32 v180, v180
	v_exp_f32_e32 v146, v146
	v_exp_f32_e32 v181, v181
	v_exp_f32_e32 v147, v147
	v_add_f32_e32 v178, 1.0, v178
	v_add_f32_e32 v144, 1.0, v144
	v_add_f32_e32 v179, 1.0, v179
	v_add_f32_e32 v145, 1.0, v145
	v_add_f32_e32 v180, 1.0, v180
	v_add_f32_e32 v146, 1.0, v146
	v_add_f32_e32 v181, 1.0, v181
	v_add_f32_e32 v147, 1.0, v147
	v_rcp_f32_e32 v178, v178
	v_rcp_f32_e32 v144, v144
	v_rcp_f32_e32 v179, v179
	v_rcp_f32_e32 v145, v145
	v_rcp_f32_e32 v180, v180
	v_rcp_f32_e32 v146, v146
	v_rcp_f32_e32 v181, v181
	v_rcp_f32_e32 v147, v147
	s_nop 0
	v_mul_f32_e32 v186, v128, v178
	v_mul_f32_e32 v187, v129, v144
	v_mul_f32_e32 v188, v130, v179
	v_mul_f32_e32 v189, v131, v145
	v_mul_f32_e32 v190, v124, v180
	v_mul_f32_e32 v191, v125, v146
	v_mul_f32_e32 v192, v126, v181
	v_mul_f32_e32 v193, v127, v147
	v_cvt_pk_bf16_f32 v144, v186, v187
	v_cvt_pk_bf16_f32 v145, v188, v189
	v_cvt_pk_bf16_f32 v146, v190, v191
	v_cvt_pk_bf16_f32 v147, v192, v193
	global_store_dwordx4 v[210:211], v[144:147], off
	v_lshlrev_b32_e32 v178, 16, v148
	v_and_b32_e32 v148, 0xffff0000, v148
	v_lshlrev_b32_e32 v179, 16, v149
	v_and_b32_e32 v149, 0xffff0000, v149
	v_lshlrev_b32_e32 v180, 16, v150
	v_and_b32_e32 v150, 0xffff0000, v150
	v_lshlrev_b32_e32 v181, 16, v151
	v_and_b32_e32 v151, 0xffff0000, v151
	v_mul_f32_e32 v178, 0xbfb8aa3b, v178
	v_mul_f32_e32 v148, 0xbfb8aa3b, v148
	v_mul_f32_e32 v179, 0xbfb8aa3b, v179
	v_mul_f32_e32 v149, 0xbfb8aa3b, v149
	v_mul_f32_e32 v180, 0xbfb8aa3b, v180
	v_mul_f32_e32 v150, 0xbfb8aa3b, v150
	v_mul_f32_e32 v181, 0xbfb8aa3b, v181
	v_mul_f32_e32 v151, 0xbfb8aa3b, v151
	v_exp_f32_e32 v178, v178
	v_exp_f32_e32 v148, v148
	v_exp_f32_e32 v179, v179
	v_exp_f32_e32 v149, v149
	v_exp_f32_e32 v180, v180
	v_exp_f32_e32 v150, v150
	v_exp_f32_e32 v181, v181
	v_exp_f32_e32 v151, v151
	v_add_f32_e32 v178, 1.0, v178
	v_add_f32_e32 v148, 1.0, v148
	v_add_f32_e32 v179, 1.0, v179
	v_add_f32_e32 v149, 1.0, v149
	v_add_f32_e32 v180, 1.0, v180
	v_add_f32_e32 v150, 1.0, v150
	v_add_f32_e32 v181, 1.0, v181
	v_add_f32_e32 v151, 1.0, v151
	v_rcp_f32_e32 v178, v178
	v_rcp_f32_e32 v148, v148
	v_rcp_f32_e32 v179, v179
	v_rcp_f32_e32 v149, v149
	v_rcp_f32_e32 v180, v180
	v_rcp_f32_e32 v150, v150
	v_rcp_f32_e32 v181, v181
	v_rcp_f32_e32 v151, v151
	s_nop 0
	v_mul_f32_e32 v186, v92, v178
	v_mul_f32_e32 v187, v93, v148
	v_mul_f32_e32 v188, v94, v179
	v_mul_f32_e32 v189, v95, v149
	v_mul_f32_e32 v190, v88, v180
	v_mul_f32_e32 v191, v89, v150
	v_mul_f32_e32 v192, v90, v181
	v_mul_f32_e32 v193, v91, v151
	v_cvt_pk_bf16_f32 v148, v186, v187
	v_cvt_pk_bf16_f32 v149, v188, v189
	v_cvt_pk_bf16_f32 v150, v190, v191
	v_cvt_pk_bf16_f32 v151, v192, v193
	global_store_dwordx4 v[210:211], v[148:151], off offset:256
	s_nop 1
	s_mov_b64 s[98:99], 0x6c000
	v_lshl_add_u64 v[210:211], v[214:215], 0, s[98:99]
	global_load_dwordx4 v[144:147], v[210:211], off
	global_load_dwordx4 v[148:151], v[210:211], off offset:256
	s_waitcnt vmcnt(4)
	s_mov_b64 s[98:99], 0x36000
	v_lshl_add_u64 v[210:211], v[216:217], 0, s[98:99]
	v_lshlrev_b32_e32 v178, 16, v152
	v_and_b32_e32 v152, 0xffff0000, v152
	v_lshlrev_b32_e32 v179, 16, v153
	v_and_b32_e32 v153, 0xffff0000, v153
	v_lshlrev_b32_e32 v180, 16, v154
	v_and_b32_e32 v154, 0xffff0000, v154
	v_lshlrev_b32_e32 v181, 16, v155
	v_and_b32_e32 v155, 0xffff0000, v155
	v_mul_f32_e32 v178, 0xbfb8aa3b, v178
	v_mul_f32_e32 v152, 0xbfb8aa3b, v152
	v_mul_f32_e32 v179, 0xbfb8aa3b, v179
	v_mul_f32_e32 v153, 0xbfb8aa3b, v153
	v_mul_f32_e32 v180, 0xbfb8aa3b, v180
	v_mul_f32_e32 v154, 0xbfb8aa3b, v154
	v_mul_f32_e32 v181, 0xbfb8aa3b, v181
	v_mul_f32_e32 v155, 0xbfb8aa3b, v155
	v_exp_f32_e32 v178, v178
	v_exp_f32_e32 v152, v152
	v_exp_f32_e32 v179, v179
	v_exp_f32_e32 v153, v153
	v_exp_f32_e32 v180, v180
	v_exp_f32_e32 v154, v154
	v_exp_f32_e32 v181, v181
	v_exp_f32_e32 v155, v155
	v_add_f32_e32 v178, 1.0, v178
	v_add_f32_e32 v152, 1.0, v152
	v_add_f32_e32 v179, 1.0, v179
	v_add_f32_e32 v153, 1.0, v153
	v_add_f32_e32 v180, 1.0, v180
	v_add_f32_e32 v154, 1.0, v154
	v_add_f32_e32 v181, 1.0, v181
	v_add_f32_e32 v155, 1.0, v155
	v_rcp_f32_e32 v178, v178
	v_rcp_f32_e32 v152, v152
	v_rcp_f32_e32 v179, v179
	v_rcp_f32_e32 v153, v153
	v_rcp_f32_e32 v180, v180
	v_rcp_f32_e32 v154, v154
	v_rcp_f32_e32 v181, v181
	v_rcp_f32_e32 v155, v155
	s_nop 0
	v_mul_f32_e32 v186, v120, v178
	v_mul_f32_e32 v187, v121, v152
	v_mul_f32_e32 v188, v122, v179
	v_mul_f32_e32 v189, v123, v153
	v_mul_f32_e32 v190, v116, v180
	v_mul_f32_e32 v191, v117, v154
	v_mul_f32_e32 v192, v118, v181
	v_mul_f32_e32 v193, v119, v155
	v_cvt_pk_bf16_f32 v152, v186, v187
	v_cvt_pk_bf16_f32 v153, v188, v189
	v_cvt_pk_bf16_f32 v154, v190, v191
	v_cvt_pk_bf16_f32 v155, v192, v193
	global_store_dwordx4 v[210:211], v[152:155], off
	v_lshlrev_b32_e32 v178, 16, v156
	v_and_b32_e32 v156, 0xffff0000, v156
	v_lshlrev_b32_e32 v179, 16, v157
	v_and_b32_e32 v157, 0xffff0000, v157
	v_lshlrev_b32_e32 v180, 16, v158
	v_and_b32_e32 v158, 0xffff0000, v158
	v_lshlrev_b32_e32 v181, 16, v159
	v_and_b32_e32 v159, 0xffff0000, v159
	v_mul_f32_e32 v178, 0xbfb8aa3b, v178
	v_mul_f32_e32 v156, 0xbfb8aa3b, v156
	v_mul_f32_e32 v179, 0xbfb8aa3b, v179
	v_mul_f32_e32 v157, 0xbfb8aa3b, v157
	v_mul_f32_e32 v180, 0xbfb8aa3b, v180
	v_mul_f32_e32 v158, 0xbfb8aa3b, v158
	v_mul_f32_e32 v181, 0xbfb8aa3b, v181
	v_mul_f32_e32 v159, 0xbfb8aa3b, v159
	v_exp_f32_e32 v178, v178
	v_exp_f32_e32 v156, v156
	v_exp_f32_e32 v179, v179
	v_exp_f32_e32 v157, v157
	v_exp_f32_e32 v180, v180
	v_exp_f32_e32 v158, v158
	v_exp_f32_e32 v181, v181
	v_exp_f32_e32 v159, v159
	v_add_f32_e32 v178, 1.0, v178
	v_add_f32_e32 v156, 1.0, v156
	v_add_f32_e32 v179, 1.0, v179
	v_add_f32_e32 v157, 1.0, v157
	v_add_f32_e32 v180, 1.0, v180
	v_add_f32_e32 v158, 1.0, v158
	v_add_f32_e32 v181, 1.0, v181
	v_add_f32_e32 v159, 1.0, v159
	v_rcp_f32_e32 v178, v178
	v_rcp_f32_e32 v156, v156
	v_rcp_f32_e32 v179, v179
	v_rcp_f32_e32 v157, v157
	v_rcp_f32_e32 v180, v180
	v_rcp_f32_e32 v158, v158
	v_rcp_f32_e32 v181, v181
	v_rcp_f32_e32 v159, v159
	s_nop 0
	v_mul_f32_e32 v186, v84, v178
	v_mul_f32_e32 v187, v85, v156
	v_mul_f32_e32 v188, v86, v179
	v_mul_f32_e32 v189, v87, v157
	v_mul_f32_e32 v190, v80, v180
	v_mul_f32_e32 v191, v81, v158
	v_mul_f32_e32 v192, v82, v181
	v_mul_f32_e32 v193, v83, v159
	v_cvt_pk_bf16_f32 v156, v186, v187
	v_cvt_pk_bf16_f32 v157, v188, v189
	v_cvt_pk_bf16_f32 v158, v190, v191
	v_cvt_pk_bf16_f32 v159, v192, v193
	global_store_dwordx4 v[210:211], v[156:159], off offset:256
	s_nop 1
	s_mov_b64 s[98:99], 0xa2000
	v_lshl_add_u64 v[210:211], v[214:215], 0, s[98:99]
	global_load_dwordx4 v[152:155], v[210:211], off
	global_load_dwordx4 v[156:159], v[210:211], off offset:256
	s_waitcnt vmcnt(4)
	s_mov_b64 s[98:99], 0x6c000
	v_lshl_add_u64 v[210:211], v[216:217], 0, s[98:99]
	v_lshlrev_b32_e32 v178, 16, v144
	v_and_b32_e32 v144, 0xffff0000, v144
	v_lshlrev_b32_e32 v179, 16, v145
	v_and_b32_e32 v145, 0xffff0000, v145
	v_lshlrev_b32_e32 v180, 16, v146
	v_and_b32_e32 v146, 0xffff0000, v146
	v_lshlrev_b32_e32 v181, 16, v147
	v_and_b32_e32 v147, 0xffff0000, v147
	v_mul_f32_e32 v178, 0xbfb8aa3b, v178
	v_mul_f32_e32 v144, 0xbfb8aa3b, v144
	v_mul_f32_e32 v179, 0xbfb8aa3b, v179
	v_mul_f32_e32 v145, 0xbfb8aa3b, v145
	v_mul_f32_e32 v180, 0xbfb8aa3b, v180
	v_mul_f32_e32 v146, 0xbfb8aa3b, v146
	v_mul_f32_e32 v181, 0xbfb8aa3b, v181
	v_mul_f32_e32 v147, 0xbfb8aa3b, v147
	v_exp_f32_e32 v178, v178
	v_exp_f32_e32 v144, v144
	v_exp_f32_e32 v179, v179
	v_exp_f32_e32 v145, v145
	v_exp_f32_e32 v180, v180
	v_exp_f32_e32 v146, v146
	v_exp_f32_e32 v181, v181
	v_exp_f32_e32 v147, v147
	v_add_f32_e32 v178, 1.0, v178
	v_add_f32_e32 v144, 1.0, v144
	v_add_f32_e32 v179, 1.0, v179
	v_add_f32_e32 v145, 1.0, v145
	v_add_f32_e32 v180, 1.0, v180
	v_add_f32_e32 v146, 1.0, v146
	v_add_f32_e32 v181, 1.0, v181
	v_add_f32_e32 v147, 1.0, v147
	v_rcp_f32_e32 v178, v178
	v_rcp_f32_e32 v144, v144
	v_rcp_f32_e32 v179, v179
	v_rcp_f32_e32 v145, v145
	v_rcp_f32_e32 v180, v180
	v_rcp_f32_e32 v146, v146
	v_rcp_f32_e32 v181, v181
	v_rcp_f32_e32 v147, v147
	s_nop 0
	v_mul_f32_e32 v186, v108, v178
	v_mul_f32_e32 v187, v109, v144
	v_mul_f32_e32 v188, v110, v179
	v_mul_f32_e32 v189, v111, v145
	v_mul_f32_e32 v190, v104, v180
	v_mul_f32_e32 v191, v105, v146
	v_mul_f32_e32 v192, v106, v181
	v_mul_f32_e32 v193, v107, v147
	v_cvt_pk_bf16_f32 v144, v186, v187
	v_cvt_pk_bf16_f32 v145, v188, v189
	v_cvt_pk_bf16_f32 v146, v190, v191
	v_cvt_pk_bf16_f32 v147, v192, v193
	global_store_dwordx4 v[210:211], v[144:147], off
	v_lshlrev_b32_e32 v178, 16, v148
	v_and_b32_e32 v148, 0xffff0000, v148
	v_lshlrev_b32_e32 v179, 16, v149
	v_and_b32_e32 v149, 0xffff0000, v149
	v_lshlrev_b32_e32 v180, 16, v150
	v_and_b32_e32 v150, 0xffff0000, v150
	v_lshlrev_b32_e32 v181, 16, v151
	v_and_b32_e32 v151, 0xffff0000, v151
	v_mul_f32_e32 v178, 0xbfb8aa3b, v178
	v_mul_f32_e32 v148, 0xbfb8aa3b, v148
	v_mul_f32_e32 v179, 0xbfb8aa3b, v179
	v_mul_f32_e32 v149, 0xbfb8aa3b, v149
	v_mul_f32_e32 v180, 0xbfb8aa3b, v180
	v_mul_f32_e32 v150, 0xbfb8aa3b, v150
	v_mul_f32_e32 v181, 0xbfb8aa3b, v181
	v_mul_f32_e32 v151, 0xbfb8aa3b, v151
	v_exp_f32_e32 v178, v178
	v_exp_f32_e32 v148, v148
	v_exp_f32_e32 v179, v179
	v_exp_f32_e32 v149, v149
	v_exp_f32_e32 v180, v180
	v_exp_f32_e32 v150, v150
	v_exp_f32_e32 v181, v181
	v_exp_f32_e32 v151, v151
	v_add_f32_e32 v178, 1.0, v178
	v_add_f32_e32 v148, 1.0, v148
	v_add_f32_e32 v179, 1.0, v179
	v_add_f32_e32 v149, 1.0, v149
	v_add_f32_e32 v180, 1.0, v180
	v_add_f32_e32 v150, 1.0, v150
	v_add_f32_e32 v181, 1.0, v181
	v_add_f32_e32 v151, 1.0, v151
	v_rcp_f32_e32 v178, v178
	v_rcp_f32_e32 v148, v148
	v_rcp_f32_e32 v179, v179
	v_rcp_f32_e32 v149, v149
	v_rcp_f32_e32 v180, v180
	v_rcp_f32_e32 v150, v150
	v_rcp_f32_e32 v181, v181
	v_rcp_f32_e32 v151, v151
	s_nop 0
	v_mul_f32_e32 v186, v76, v178
	v_mul_f32_e32 v187, v77, v148
	v_mul_f32_e32 v188, v78, v179
	v_mul_f32_e32 v189, v79, v149
	v_mul_f32_e32 v190, v72, v180
	v_mul_f32_e32 v191, v73, v150
	v_mul_f32_e32 v192, v74, v181
	v_mul_f32_e32 v193, v75, v151
	v_cvt_pk_bf16_f32 v148, v186, v187
	v_cvt_pk_bf16_f32 v149, v188, v189
	v_cvt_pk_bf16_f32 v150, v190, v191
	v_cvt_pk_bf16_f32 v151, v192, v193
	global_store_dwordx4 v[210:211], v[148:151], off offset:256
	s_nop 1
	s_mov_b64 s[98:99], 0x1b0000
	v_lshl_add_u64 v[210:211], v[214:215], 0, s[98:99]
	global_load_dwordx4 v[144:147], v[210:211], off
	global_load_dwordx4 v[148:151], v[210:211], off offset:256
	s_waitcnt vmcnt(4)
	s_mov_b64 s[98:99], 0xa2000
	v_lshl_add_u64 v[210:211], v[216:217], 0, s[98:99]
	v_lshlrev_b32_e32 v178, 16, v152
	v_and_b32_e32 v152, 0xffff0000, v152
	v_lshlrev_b32_e32 v179, 16, v153
	v_and_b32_e32 v153, 0xffff0000, v153
	v_lshlrev_b32_e32 v180, 16, v154
	v_and_b32_e32 v154, 0xffff0000, v154
	v_lshlrev_b32_e32 v181, 16, v155
	v_and_b32_e32 v155, 0xffff0000, v155
	v_mul_f32_e32 v178, 0xbfb8aa3b, v178
	v_mul_f32_e32 v152, 0xbfb8aa3b, v152
	v_mul_f32_e32 v179, 0xbfb8aa3b, v179
	v_mul_f32_e32 v153, 0xbfb8aa3b, v153
	v_mul_f32_e32 v180, 0xbfb8aa3b, v180
	v_mul_f32_e32 v154, 0xbfb8aa3b, v154
	v_mul_f32_e32 v181, 0xbfb8aa3b, v181
	v_mul_f32_e32 v155, 0xbfb8aa3b, v155
	v_exp_f32_e32 v178, v178
	v_exp_f32_e32 v152, v152
	v_exp_f32_e32 v179, v179
	v_exp_f32_e32 v153, v153
	v_exp_f32_e32 v180, v180
	v_exp_f32_e32 v154, v154
	v_exp_f32_e32 v181, v181
	v_exp_f32_e32 v155, v155
	v_add_f32_e32 v178, 1.0, v178
	v_add_f32_e32 v152, 1.0, v152
	v_add_f32_e32 v179, 1.0, v179
	v_add_f32_e32 v153, 1.0, v153
	v_add_f32_e32 v180, 1.0, v180
	v_add_f32_e32 v154, 1.0, v154
	v_add_f32_e32 v181, 1.0, v181
	v_add_f32_e32 v155, 1.0, v155
	v_rcp_f32_e32 v178, v178
	v_rcp_f32_e32 v152, v152
	v_rcp_f32_e32 v179, v179
	v_rcp_f32_e32 v153, v153
	v_rcp_f32_e32 v180, v180
	v_rcp_f32_e32 v154, v154
	v_rcp_f32_e32 v181, v181
	v_rcp_f32_e32 v155, v155
	s_nop 0
	v_mul_f32_e32 v186, v100, v178
	v_mul_f32_e32 v187, v101, v152
	v_mul_f32_e32 v188, v102, v179
	v_mul_f32_e32 v189, v103, v153
	v_mul_f32_e32 v190, v96, v180
	v_mul_f32_e32 v191, v97, v154
	v_mul_f32_e32 v192, v98, v181
	v_mul_f32_e32 v193, v99, v155
	v_cvt_pk_bf16_f32 v152, v186, v187
	v_cvt_pk_bf16_f32 v153, v188, v189
	v_cvt_pk_bf16_f32 v154, v190, v191
	v_cvt_pk_bf16_f32 v155, v192, v193
	global_store_dwordx4 v[210:211], v[152:155], off
	v_lshlrev_b32_e32 v178, 16, v156
	v_and_b32_e32 v156, 0xffff0000, v156
	v_lshlrev_b32_e32 v179, 16, v157
	v_and_b32_e32 v157, 0xffff0000, v157
	v_lshlrev_b32_e32 v180, 16, v158
	v_and_b32_e32 v158, 0xffff0000, v158
	v_lshlrev_b32_e32 v181, 16, v159
	v_and_b32_e32 v159, 0xffff0000, v159
	v_mul_f32_e32 v178, 0xbfb8aa3b, v178
	v_mul_f32_e32 v156, 0xbfb8aa3b, v156
	v_mul_f32_e32 v179, 0xbfb8aa3b, v179
	v_mul_f32_e32 v157, 0xbfb8aa3b, v157
	v_mul_f32_e32 v180, 0xbfb8aa3b, v180
	v_mul_f32_e32 v158, 0xbfb8aa3b, v158
	v_mul_f32_e32 v181, 0xbfb8aa3b, v181
	v_mul_f32_e32 v159, 0xbfb8aa3b, v159
	v_exp_f32_e32 v178, v178
	v_exp_f32_e32 v156, v156
	v_exp_f32_e32 v179, v179
	v_exp_f32_e32 v157, v157
	v_exp_f32_e32 v180, v180
	v_exp_f32_e32 v158, v158
	v_exp_f32_e32 v181, v181
	v_exp_f32_e32 v159, v159
	v_add_f32_e32 v178, 1.0, v178
	v_add_f32_e32 v156, 1.0, v156
	v_add_f32_e32 v179, 1.0, v179
	v_add_f32_e32 v157, 1.0, v157
	v_add_f32_e32 v180, 1.0, v180
	v_add_f32_e32 v158, 1.0, v158
	v_add_f32_e32 v181, 1.0, v181
	v_add_f32_e32 v159, 1.0, v159
	v_rcp_f32_e32 v178, v178
	v_rcp_f32_e32 v156, v156
	v_rcp_f32_e32 v179, v179
	v_rcp_f32_e32 v157, v157
	v_rcp_f32_e32 v180, v180
	v_rcp_f32_e32 v158, v158
	v_rcp_f32_e32 v181, v181
	v_rcp_f32_e32 v159, v159
	s_nop 0
	v_mul_f32_e32 v186, v68, v178
	v_mul_f32_e32 v187, v69, v156
	v_mul_f32_e32 v188, v70, v179
	v_mul_f32_e32 v189, v71, v157
	v_mul_f32_e32 v190, v64, v180
	v_mul_f32_e32 v191, v65, v158
	v_mul_f32_e32 v192, v66, v181
	v_mul_f32_e32 v193, v67, v159
	v_cvt_pk_bf16_f32 v156, v186, v187
	v_cvt_pk_bf16_f32 v157, v188, v189
	v_cvt_pk_bf16_f32 v158, v190, v191
	v_cvt_pk_bf16_f32 v159, v192, v193
	global_store_dwordx4 v[210:211], v[156:159], off offset:256
	s_nop 1
	s_mov_b64 s[98:99], 0x1e6000
	v_lshl_add_u64 v[210:211], v[214:215], 0, s[98:99]
	global_load_dwordx4 v[152:155], v[210:211], off
	global_load_dwordx4 v[156:159], v[210:211], off offset:256
	s_waitcnt vmcnt(4)
	s_mov_b64 s[98:99], 0x1b0000
	v_lshl_add_u64 v[210:211], v[216:217], 0, s[98:99]
	v_lshlrev_b32_e32 v178, 16, v144
	v_and_b32_e32 v144, 0xffff0000, v144
	v_lshlrev_b32_e32 v179, 16, v145
	v_and_b32_e32 v145, 0xffff0000, v145
	v_lshlrev_b32_e32 v180, 16, v146
	v_and_b32_e32 v146, 0xffff0000, v146
	v_lshlrev_b32_e32 v181, 16, v147
	v_and_b32_e32 v147, 0xffff0000, v147
	v_mul_f32_e32 v178, 0xbfb8aa3b, v178
	v_mul_f32_e32 v144, 0xbfb8aa3b, v144
	v_mul_f32_e32 v179, 0xbfb8aa3b, v179
	v_mul_f32_e32 v145, 0xbfb8aa3b, v145
	v_mul_f32_e32 v180, 0xbfb8aa3b, v180
	v_mul_f32_e32 v146, 0xbfb8aa3b, v146
	v_mul_f32_e32 v181, 0xbfb8aa3b, v181
	v_mul_f32_e32 v147, 0xbfb8aa3b, v147
	v_exp_f32_e32 v178, v178
	v_exp_f32_e32 v144, v144
	v_exp_f32_e32 v179, v179
	v_exp_f32_e32 v145, v145
	v_exp_f32_e32 v180, v180
	v_exp_f32_e32 v146, v146
	v_exp_f32_e32 v181, v181
	v_exp_f32_e32 v147, v147
	v_add_f32_e32 v178, 1.0, v178
	v_add_f32_e32 v144, 1.0, v144
	v_add_f32_e32 v179, 1.0, v179
	v_add_f32_e32 v145, 1.0, v145
	v_add_f32_e32 v180, 1.0, v180
	v_add_f32_e32 v146, 1.0, v146
	v_add_f32_e32 v181, 1.0, v181
	v_add_f32_e32 v147, 1.0, v147
	v_rcp_f32_e32 v178, v178
	v_rcp_f32_e32 v144, v144
	v_rcp_f32_e32 v179, v179
	v_rcp_f32_e32 v145, v145
	v_rcp_f32_e32 v180, v180
	v_rcp_f32_e32 v146, v146
	v_rcp_f32_e32 v181, v181
	v_rcp_f32_e32 v147, v147
	s_nop 0
	v_mul_f32_e32 v186, v60, v178
	v_mul_f32_e32 v187, v61, v144
	v_mul_f32_e32 v188, v62, v179
	v_mul_f32_e32 v189, v63, v145
	v_mul_f32_e32 v190, v56, v180
	v_mul_f32_e32 v191, v57, v146
	v_mul_f32_e32 v192, v58, v181
	v_mul_f32_e32 v193, v59, v147
	v_cvt_pk_bf16_f32 v144, v186, v187
	v_cvt_pk_bf16_f32 v145, v188, v189
	v_cvt_pk_bf16_f32 v146, v190, v191
	v_cvt_pk_bf16_f32 v147, v192, v193
	global_store_dwordx4 v[210:211], v[144:147], off
	v_lshlrev_b32_e32 v178, 16, v148
	v_and_b32_e32 v148, 0xffff0000, v148
	v_lshlrev_b32_e32 v179, 16, v149
	v_and_b32_e32 v149, 0xffff0000, v149
	v_lshlrev_b32_e32 v180, 16, v150
	v_and_b32_e32 v150, 0xffff0000, v150
	v_lshlrev_b32_e32 v181, 16, v151
	v_and_b32_e32 v151, 0xffff0000, v151
	v_mul_f32_e32 v178, 0xbfb8aa3b, v178
	v_mul_f32_e32 v148, 0xbfb8aa3b, v148
	v_mul_f32_e32 v179, 0xbfb8aa3b, v179
	v_mul_f32_e32 v149, 0xbfb8aa3b, v149
	v_mul_f32_e32 v180, 0xbfb8aa3b, v180
	v_mul_f32_e32 v150, 0xbfb8aa3b, v150
	v_mul_f32_e32 v181, 0xbfb8aa3b, v181
	v_mul_f32_e32 v151, 0xbfb8aa3b, v151
	v_exp_f32_e32 v178, v178
	v_exp_f32_e32 v148, v148
	v_exp_f32_e32 v179, v179
	v_exp_f32_e32 v149, v149
	v_exp_f32_e32 v180, v180
	v_exp_f32_e32 v150, v150
	v_exp_f32_e32 v181, v181
	v_exp_f32_e32 v151, v151
	v_add_f32_e32 v178, 1.0, v178
	v_add_f32_e32 v148, 1.0, v148
	v_add_f32_e32 v179, 1.0, v179
	v_add_f32_e32 v149, 1.0, v149
	v_add_f32_e32 v180, 1.0, v180
	v_add_f32_e32 v150, 1.0, v150
	v_add_f32_e32 v181, 1.0, v181
	v_add_f32_e32 v151, 1.0, v151
	v_rcp_f32_e32 v178, v178
	v_rcp_f32_e32 v148, v148
	v_rcp_f32_e32 v179, v179
	v_rcp_f32_e32 v149, v149
	v_rcp_f32_e32 v180, v180
	v_rcp_f32_e32 v150, v150
	v_rcp_f32_e32 v181, v181
	v_rcp_f32_e32 v151, v151
	s_nop 0
	v_mul_f32_e32 v186, v28, v178
	v_mul_f32_e32 v187, v29, v148
	v_mul_f32_e32 v188, v30, v179
	v_mul_f32_e32 v189, v31, v149
	v_mul_f32_e32 v190, v24, v180
	v_mul_f32_e32 v191, v25, v150
	v_mul_f32_e32 v192, v26, v181
	v_mul_f32_e32 v193, v27, v151
	v_cvt_pk_bf16_f32 v148, v186, v187
	v_cvt_pk_bf16_f32 v149, v188, v189
	v_cvt_pk_bf16_f32 v150, v190, v191
	v_cvt_pk_bf16_f32 v151, v192, v193
	global_store_dwordx4 v[210:211], v[148:151], off offset:256
	s_nop 1
	s_mov_b64 s[98:99], 0x21c000
	v_lshl_add_u64 v[210:211], v[214:215], 0, s[98:99]
	global_load_dwordx4 v[144:147], v[210:211], off
	global_load_dwordx4 v[148:151], v[210:211], off offset:256
	s_waitcnt vmcnt(4)
	s_mov_b64 s[98:99], 0x1e6000
	v_lshl_add_u64 v[210:211], v[216:217], 0, s[98:99]
	v_lshlrev_b32_e32 v178, 16, v152
	v_and_b32_e32 v152, 0xffff0000, v152
	v_lshlrev_b32_e32 v179, 16, v153
	v_and_b32_e32 v153, 0xffff0000, v153
	v_lshlrev_b32_e32 v180, 16, v154
	v_and_b32_e32 v154, 0xffff0000, v154
	v_lshlrev_b32_e32 v181, 16, v155
	v_and_b32_e32 v155, 0xffff0000, v155
	v_mul_f32_e32 v178, 0xbfb8aa3b, v178
	v_mul_f32_e32 v152, 0xbfb8aa3b, v152
	v_mul_f32_e32 v179, 0xbfb8aa3b, v179
	v_mul_f32_e32 v153, 0xbfb8aa3b, v153
	v_mul_f32_e32 v180, 0xbfb8aa3b, v180
	v_mul_f32_e32 v154, 0xbfb8aa3b, v154
	v_mul_f32_e32 v181, 0xbfb8aa3b, v181
	v_mul_f32_e32 v155, 0xbfb8aa3b, v155
	v_exp_f32_e32 v178, v178
	v_exp_f32_e32 v152, v152
	v_exp_f32_e32 v179, v179
	v_exp_f32_e32 v153, v153
	v_exp_f32_e32 v180, v180
	v_exp_f32_e32 v154, v154
	v_exp_f32_e32 v181, v181
	v_exp_f32_e32 v155, v155
	v_add_f32_e32 v178, 1.0, v178
	v_add_f32_e32 v152, 1.0, v152
	v_add_f32_e32 v179, 1.0, v179
	v_add_f32_e32 v153, 1.0, v153
	v_add_f32_e32 v180, 1.0, v180
	v_add_f32_e32 v154, 1.0, v154
	v_add_f32_e32 v181, 1.0, v181
	v_add_f32_e32 v155, 1.0, v155
	v_rcp_f32_e32 v178, v178
	v_rcp_f32_e32 v152, v152
	v_rcp_f32_e32 v179, v179
	v_rcp_f32_e32 v153, v153
	v_rcp_f32_e32 v180, v180
	v_rcp_f32_e32 v154, v154
	v_rcp_f32_e32 v181, v181
	v_rcp_f32_e32 v155, v155
	s_nop 0
	v_mul_f32_e32 v186, v52, v178
	v_mul_f32_e32 v187, v53, v152
	v_mul_f32_e32 v188, v54, v179
	v_mul_f32_e32 v189, v55, v153
	v_mul_f32_e32 v190, v48, v180
	v_mul_f32_e32 v191, v49, v154
	v_mul_f32_e32 v192, v50, v181
	v_mul_f32_e32 v193, v51, v155
	v_cvt_pk_bf16_f32 v152, v186, v187
	v_cvt_pk_bf16_f32 v153, v188, v189
	v_cvt_pk_bf16_f32 v154, v190, v191
	v_cvt_pk_bf16_f32 v155, v192, v193
	global_store_dwordx4 v[210:211], v[152:155], off
	v_lshlrev_b32_e32 v178, 16, v156
	v_and_b32_e32 v156, 0xffff0000, v156
	v_lshlrev_b32_e32 v179, 16, v157
	v_and_b32_e32 v157, 0xffff0000, v157
	v_lshlrev_b32_e32 v180, 16, v158
	v_and_b32_e32 v158, 0xffff0000, v158
	v_lshlrev_b32_e32 v181, 16, v159
	v_and_b32_e32 v159, 0xffff0000, v159
	v_mul_f32_e32 v178, 0xbfb8aa3b, v178
	v_mul_f32_e32 v156, 0xbfb8aa3b, v156
	v_mul_f32_e32 v179, 0xbfb8aa3b, v179
	v_mul_f32_e32 v157, 0xbfb8aa3b, v157
	v_mul_f32_e32 v180, 0xbfb8aa3b, v180
	v_mul_f32_e32 v158, 0xbfb8aa3b, v158
	v_mul_f32_e32 v181, 0xbfb8aa3b, v181
	v_mul_f32_e32 v159, 0xbfb8aa3b, v159
	v_exp_f32_e32 v178, v178
	v_exp_f32_e32 v156, v156
	v_exp_f32_e32 v179, v179
	v_exp_f32_e32 v157, v157
	v_exp_f32_e32 v180, v180
	v_exp_f32_e32 v158, v158
	v_exp_f32_e32 v181, v181
	v_exp_f32_e32 v159, v159
	v_add_f32_e32 v178, 1.0, v178
	v_add_f32_e32 v156, 1.0, v156
	v_add_f32_e32 v179, 1.0, v179
	v_add_f32_e32 v157, 1.0, v157
	v_add_f32_e32 v180, 1.0, v180
	v_add_f32_e32 v158, 1.0, v158
	v_add_f32_e32 v181, 1.0, v181
	v_add_f32_e32 v159, 1.0, v159
	v_rcp_f32_e32 v178, v178
	v_rcp_f32_e32 v156, v156
	v_rcp_f32_e32 v179, v179
	v_rcp_f32_e32 v157, v157
	v_rcp_f32_e32 v180, v180
	v_rcp_f32_e32 v158, v158
	v_rcp_f32_e32 v181, v181
	v_rcp_f32_e32 v159, v159
	s_nop 0
	v_mul_f32_e32 v186, v20, v178
	v_mul_f32_e32 v187, v21, v156
	v_mul_f32_e32 v188, v22, v179
	v_mul_f32_e32 v189, v23, v157
	v_mul_f32_e32 v190, v16, v180
	v_mul_f32_e32 v191, v17, v158
	v_mul_f32_e32 v192, v18, v181
	v_mul_f32_e32 v193, v19, v159
	v_cvt_pk_bf16_f32 v156, v186, v187
	v_cvt_pk_bf16_f32 v157, v188, v189
	v_cvt_pk_bf16_f32 v158, v190, v191
	v_cvt_pk_bf16_f32 v159, v192, v193
	global_store_dwordx4 v[210:211], v[156:159], off offset:256
	s_nop 1
	s_mov_b64 s[98:99], 0x252000
	v_lshl_add_u64 v[210:211], v[214:215], 0, s[98:99]
	global_load_dwordx4 v[152:155], v[210:211], off
	global_load_dwordx4 v[156:159], v[210:211], off offset:256
	s_waitcnt vmcnt(4)
	s_mov_b64 s[98:99], 0x21c000
	v_lshl_add_u64 v[210:211], v[216:217], 0, s[98:99]
	v_lshlrev_b32_e32 v178, 16, v144
	v_and_b32_e32 v144, 0xffff0000, v144
	v_lshlrev_b32_e32 v179, 16, v145
	v_and_b32_e32 v145, 0xffff0000, v145
	v_lshlrev_b32_e32 v180, 16, v146
	v_and_b32_e32 v146, 0xffff0000, v146
	v_lshlrev_b32_e32 v181, 16, v147
	v_and_b32_e32 v147, 0xffff0000, v147
	v_mul_f32_e32 v178, 0xbfb8aa3b, v178
	v_mul_f32_e32 v144, 0xbfb8aa3b, v144
	v_mul_f32_e32 v179, 0xbfb8aa3b, v179
	v_mul_f32_e32 v145, 0xbfb8aa3b, v145
	v_mul_f32_e32 v180, 0xbfb8aa3b, v180
	v_mul_f32_e32 v146, 0xbfb8aa3b, v146
	v_mul_f32_e32 v181, 0xbfb8aa3b, v181
	v_mul_f32_e32 v147, 0xbfb8aa3b, v147
	v_exp_f32_e32 v178, v178
	v_exp_f32_e32 v144, v144
	v_exp_f32_e32 v179, v179
	v_exp_f32_e32 v145, v145
	v_exp_f32_e32 v180, v180
	v_exp_f32_e32 v146, v146
	v_exp_f32_e32 v181, v181
	v_exp_f32_e32 v147, v147
	v_add_f32_e32 v178, 1.0, v178
	v_add_f32_e32 v144, 1.0, v144
	v_add_f32_e32 v179, 1.0, v179
	v_add_f32_e32 v145, 1.0, v145
	v_add_f32_e32 v180, 1.0, v180
	v_add_f32_e32 v146, 1.0, v146
	v_add_f32_e32 v181, 1.0, v181
	v_add_f32_e32 v147, 1.0, v147
	v_rcp_f32_e32 v178, v178
	v_rcp_f32_e32 v144, v144
	v_rcp_f32_e32 v179, v179
	v_rcp_f32_e32 v145, v145
	v_rcp_f32_e32 v180, v180
	v_rcp_f32_e32 v146, v146
	v_rcp_f32_e32 v181, v181
	v_rcp_f32_e32 v147, v147
	s_nop 0
	v_mul_f32_e32 v186, v44, v178
	v_mul_f32_e32 v187, v45, v144
	v_mul_f32_e32 v188, v46, v179
	v_mul_f32_e32 v189, v47, v145
	v_mul_f32_e32 v190, v40, v180
	v_mul_f32_e32 v191, v41, v146
	v_mul_f32_e32 v192, v42, v181
	v_mul_f32_e32 v193, v43, v147
	v_cvt_pk_bf16_f32 v144, v186, v187
	v_cvt_pk_bf16_f32 v145, v188, v189
	v_cvt_pk_bf16_f32 v146, v190, v191
	v_cvt_pk_bf16_f32 v147, v192, v193
	global_store_dwordx4 v[210:211], v[144:147], off
	v_lshlrev_b32_e32 v178, 16, v148
	v_and_b32_e32 v148, 0xffff0000, v148
	v_lshlrev_b32_e32 v179, 16, v149
	v_and_b32_e32 v149, 0xffff0000, v149
	v_lshlrev_b32_e32 v180, 16, v150
	v_and_b32_e32 v150, 0xffff0000, v150
	v_lshlrev_b32_e32 v181, 16, v151
	v_and_b32_e32 v151, 0xffff0000, v151
	v_mul_f32_e32 v178, 0xbfb8aa3b, v178
	v_mul_f32_e32 v148, 0xbfb8aa3b, v148
	v_mul_f32_e32 v179, 0xbfb8aa3b, v179
	v_mul_f32_e32 v149, 0xbfb8aa3b, v149
	v_mul_f32_e32 v180, 0xbfb8aa3b, v180
	v_mul_f32_e32 v150, 0xbfb8aa3b, v150
	v_mul_f32_e32 v181, 0xbfb8aa3b, v181
	v_mul_f32_e32 v151, 0xbfb8aa3b, v151
	v_exp_f32_e32 v178, v178
	v_exp_f32_e32 v148, v148
	v_exp_f32_e32 v179, v179
	v_exp_f32_e32 v149, v149
	v_exp_f32_e32 v180, v180
	v_exp_f32_e32 v150, v150
	v_exp_f32_e32 v181, v181
	v_exp_f32_e32 v151, v151
	v_add_f32_e32 v178, 1.0, v178
	v_add_f32_e32 v148, 1.0, v148
	v_add_f32_e32 v179, 1.0, v179
	v_add_f32_e32 v149, 1.0, v149
	v_add_f32_e32 v180, 1.0, v180
	v_add_f32_e32 v150, 1.0, v150
	v_add_f32_e32 v181, 1.0, v181
	v_add_f32_e32 v151, 1.0, v151
	v_rcp_f32_e32 v178, v178
	v_rcp_f32_e32 v148, v148
	v_rcp_f32_e32 v179, v179
	v_rcp_f32_e32 v149, v149
	v_rcp_f32_e32 v180, v180
	v_rcp_f32_e32 v150, v150
	v_rcp_f32_e32 v181, v181
	v_rcp_f32_e32 v151, v151
	s_nop 0
	v_mul_f32_e32 v186, v12, v178
	v_mul_f32_e32 v187, v13, v148
	v_mul_f32_e32 v188, v14, v179
	v_mul_f32_e32 v189, v15, v149
	v_mul_f32_e32 v190, v8, v180
	v_mul_f32_e32 v191, v9, v150
	v_mul_f32_e32 v192, v10, v181
	v_mul_f32_e32 v193, v11, v151
	v_cvt_pk_bf16_f32 v148, v186, v187
	v_cvt_pk_bf16_f32 v149, v188, v189
	v_cvt_pk_bf16_f32 v150, v190, v191
	v_cvt_pk_bf16_f32 v151, v192, v193
	global_store_dwordx4 v[210:211], v[148:151], off offset:256
	s_waitcnt vmcnt(2)
	s_mov_b64 s[98:99], 0x252000
	v_lshl_add_u64 v[210:211], v[216:217], 0, s[98:99]
	v_lshlrev_b32_e32 v178, 16, v152
	v_and_b32_e32 v152, 0xffff0000, v152
	v_lshlrev_b32_e32 v179, 16, v153
	v_and_b32_e32 v153, 0xffff0000, v153
	v_lshlrev_b32_e32 v180, 16, v154
	v_and_b32_e32 v154, 0xffff0000, v154
	v_lshlrev_b32_e32 v181, 16, v155
	v_and_b32_e32 v155, 0xffff0000, v155
	v_mul_f32_e32 v178, 0xbfb8aa3b, v178
	v_mul_f32_e32 v152, 0xbfb8aa3b, v152
	v_mul_f32_e32 v179, 0xbfb8aa3b, v179
	v_mul_f32_e32 v153, 0xbfb8aa3b, v153
	v_mul_f32_e32 v180, 0xbfb8aa3b, v180
	v_mul_f32_e32 v154, 0xbfb8aa3b, v154
	v_mul_f32_e32 v181, 0xbfb8aa3b, v181
	v_mul_f32_e32 v155, 0xbfb8aa3b, v155
	v_exp_f32_e32 v178, v178
	v_exp_f32_e32 v152, v152
	v_exp_f32_e32 v179, v179
	v_exp_f32_e32 v153, v153
	v_exp_f32_e32 v180, v180
	v_exp_f32_e32 v154, v154
	v_exp_f32_e32 v181, v181
	v_exp_f32_e32 v155, v155
	v_add_f32_e32 v178, 1.0, v178
	v_add_f32_e32 v152, 1.0, v152
	v_add_f32_e32 v179, 1.0, v179
	v_add_f32_e32 v153, 1.0, v153
	v_add_f32_e32 v180, 1.0, v180
	v_add_f32_e32 v154, 1.0, v154
	v_add_f32_e32 v181, 1.0, v181
	v_add_f32_e32 v155, 1.0, v155
	v_rcp_f32_e32 v178, v178
	v_rcp_f32_e32 v152, v152
	v_rcp_f32_e32 v179, v179
	v_rcp_f32_e32 v153, v153
	v_rcp_f32_e32 v180, v180
	v_rcp_f32_e32 v154, v154
	v_rcp_f32_e32 v181, v181
	v_rcp_f32_e32 v155, v155
	s_nop 0
	v_mul_f32_e32 v186, v36, v178
	v_mul_f32_e32 v187, v37, v152
	v_mul_f32_e32 v188, v38, v179
	v_mul_f32_e32 v189, v39, v153
	v_mul_f32_e32 v190, v32, v180
	v_mul_f32_e32 v191, v33, v154
	v_mul_f32_e32 v192, v34, v181
	v_mul_f32_e32 v193, v35, v155
	v_cvt_pk_bf16_f32 v152, v186, v187
	v_cvt_pk_bf16_f32 v153, v188, v189
	v_cvt_pk_bf16_f32 v154, v190, v191
	v_cvt_pk_bf16_f32 v155, v192, v193
	global_store_dwordx4 v[210:211], v[152:155], off
	v_lshlrev_b32_e32 v178, 16, v156
	v_and_b32_e32 v156, 0xffff0000, v156
	v_lshlrev_b32_e32 v179, 16, v157
	v_and_b32_e32 v157, 0xffff0000, v157
	v_lshlrev_b32_e32 v180, 16, v158
	v_and_b32_e32 v158, 0xffff0000, v158
	v_lshlrev_b32_e32 v181, 16, v159
	v_and_b32_e32 v159, 0xffff0000, v159
	v_mul_f32_e32 v178, 0xbfb8aa3b, v178
	v_mul_f32_e32 v156, 0xbfb8aa3b, v156
	v_mul_f32_e32 v179, 0xbfb8aa3b, v179
	v_mul_f32_e32 v157, 0xbfb8aa3b, v157
	v_mul_f32_e32 v180, 0xbfb8aa3b, v180
	v_mul_f32_e32 v158, 0xbfb8aa3b, v158
	v_mul_f32_e32 v181, 0xbfb8aa3b, v181
	v_mul_f32_e32 v159, 0xbfb8aa3b, v159
	v_exp_f32_e32 v178, v178
	v_exp_f32_e32 v156, v156
	v_exp_f32_e32 v179, v179
	v_exp_f32_e32 v157, v157
	v_exp_f32_e32 v180, v180
	v_exp_f32_e32 v158, v158
	v_exp_f32_e32 v181, v181
	v_exp_f32_e32 v159, v159
	v_add_f32_e32 v178, 1.0, v178
	v_add_f32_e32 v156, 1.0, v156
	v_add_f32_e32 v179, 1.0, v179
	v_add_f32_e32 v157, 1.0, v157
	v_add_f32_e32 v180, 1.0, v180
	v_add_f32_e32 v158, 1.0, v158
	v_add_f32_e32 v181, 1.0, v181
	v_add_f32_e32 v159, 1.0, v159
	v_rcp_f32_e32 v178, v178
	v_rcp_f32_e32 v156, v156
	v_rcp_f32_e32 v179, v179
	v_rcp_f32_e32 v157, v157
	v_rcp_f32_e32 v180, v180
	v_rcp_f32_e32 v158, v158
	v_rcp_f32_e32 v181, v181
	v_rcp_f32_e32 v159, v159
	s_nop 0
	v_mul_f32_e32 v186, v4, v178
	v_mul_f32_e32 v187, v5, v156
	v_mul_f32_e32 v188, v6, v179
	v_mul_f32_e32 v189, v7, v157
	v_mul_f32_e32 v190, v0, v180
	v_mul_f32_e32 v191, v1, v158
	v_mul_f32_e32 v192, v2, v181
	v_mul_f32_e32 v193, v3, v159
	v_cvt_pk_bf16_f32 v156, v186, v187
	v_cvt_pk_bf16_f32 v157, v188, v189
	v_cvt_pk_bf16_f32 v158, v190, v191
	v_cvt_pk_bf16_f32 v159, v192, v193
	global_store_dwordx4 v[210:211], v[156:159], off offset:256
	v_readlane_b32 s98, v254, 40
	s_nop 3
	s_cmp_lg_u32 s98, 0
	s_cbranch_scc1 .Lmgepi_done
	s_cmp_lg_u32 s86, 0x100
	s_cbranch_scc1 .Lmgepi_done
	s_waitcnt vmcnt(0)
	s_mov_b64 s[6:7], exec
	s_mov_b64 exec, 1
	v_mov_b32_e32 v178, 0x22320
	v_mov_b32_e32 v179, 1
	ds_add_rtn_u32 v178, v178, v179
	s_waitcnt lgkmcnt(0)
	v_readfirstlane_b32 s98, v178
	s_and_b32 s98, s98, 7
	s_cmp_lg_u32 s98, 7
	s_cbranch_scc1 .Lmgepi_pub_skip
	v_readlane_b32 s98, v255, 30
	s_nop 3
	s_cmp_lg_u32 s98, 0
	s_cselect_b32 s100, 0x200, 0
	s_cmp_ge_u32 s58, 6
	s_cbranch_scc1 .Lmgepi_pub_r2
	s_lshr_b32 s101, s100, 7
	v_readlane_b32 s98, v253, 3
	v_readlane_b32 s99, v253, 4
	s_nop 3
	s_add_u32 s98, s98, s101
	s_addc_u32 s99, s99, 0
	s_nop 4
	global_atomic_add v178, v113, v179, s[98:99] offset:64 sc0
	v_mov_b32_e32 v180, 0x22300
	ds_read_b32 v180, v180
	s_waitcnt vmcnt(0) lgkmcnt(0)
	v_add_u32_e32 v178, 1, v178
	v_cmp_eq_u32_e32 vcc, v178, v180
	s_cbranch_vccz .Lmgepi_pub_skip
	buffer_wbl2 sc1
	s_waitcnt vmcnt(0)
	s_add_u32 s100, s100, 0x8000
	s_add_u32 s98, s88, s100
	s_addc_u32 s99, s89, 0
	s_nop 4
	global_atomic_add v113, v179, s[98:99]
	s_branch .Lmgepi_pub_skip
